# GEMM loops: the setprio 0/1 flip between the two MFMA groups of each compute segment removed (priority held across the segment)
# speedup vs baseline: 1.0050x; 1.0050x over previous
; #define PG8_STAGE(bufoff, gbase, voff) do { _Pragma("unroll") for (int _i = 0; _i < 2; ++_i) \
;         __builtin_amdgcn_global_load_lds((const unsigned*)((const char*)(gbase) + (voff)[_i]), (LAS unsigned*)(lds + (bufoff) + ldsw + _i * 8192), 16, 0, 0); } while (0)
; #define PG8_LDA(dst, b, h) do { _Pragma("unroll") for (int m = 0; m < 4; ++m) _Pragma("unroll") for (int k = 0; k < 2; ++k) dst[m][k] = *(const LAS bf16x8*)(lds + PG8_SA(b, h) + aoff + m * 2048 + k * 1024); } while (0)
; #define PG8_LDB(dst, b, h) do { _Pragma("unroll") for (int n = 0; n < 2; ++n) _Pragma("unroll") for (int k = 0; k < 2; ++k) dst[n][k] = *(const LAS bf16x8*)(lds + PG8_SB(b, h) + boff + n * 2048 + k * 1024); } while (0)
; #define PG8_WAIT_V(n) asm volatile("s_waitcnt vmcnt(" #n ")" ::: "memory")
; #define PG8_WAIT_L(n) asm volatile("s_waitcnt lgkmcnt(" #n ")" ::: "memory")
; #define PG8_BAR __builtin_amdgcn_s_barrier()
; #define PG8_SCHED __builtin_amdgcn_sched_barrier(0)
; template <class Epi, class Sched, bool F8 = false>
; __device__ __forceinline__ void gemm_phase(LAS unsigned char* lds, const Gemm g, const Sched& S, const Epi& E) {
;     ...
;             const bool last = (t == nt - 2);
;             const char* a1 = cA + (size_t)(t + 1) * kstep;
;             const char* a2 = last ? nA : cA + (size_t)(t + 2) * kstep; const char* b2 = last ? nB : cB + (size_t)(t + 2) * kstep;
;             const char* a3 = a2 + kstep; const char* b3 = b2 + kstep;
;             PG8_LDB(B0, 0, 0); PG8_LDB(B1, 0, 1); PG8_SCHED; PG8_LDA(At, 0, 0); PG8_STAGE(PG8_SA(1, 1), a1 + hstepA, voffA);
;             PG8_WAIT_V(8); PG8_WAIT_L(0); PG8_BAR; PG8_MMA(0, 0, At, B0); PG8_MMA(0, 1, At, B1); PG8_BAR; PG8_SCHED;
;             PG8_LDA(At, 0, 1); PG8_STAGE(PG8_SB(0, 0), b2, voffB); PG8_STAGE(PG8_SB(0, 1), b2 + hstepB, voffB); PG8_STAGE(PG8_SA(0, 0), a2, voffA);
;             PG8_WAIT_V(8); PG8_WAIT_L(0); PG8_BAR; PG8_MMA(1, 0, At, B0); PG8_MMA(1, 1, At, B1); PG8_BAR; PG8_SCHED;
;             PG8_LDB(B0, 1, 0); PG8_LDB(B1, 1, 1); PG8_SCHED; PG8_LDA(At, 1, 0); PG8_STAGE(PG8_SA(0, 1), a2 + hstepA, voffA);
;             PG8_WAIT_V(8); PG8_WAIT_L(0); PG8_BAR; PG8_MMA(0, 0, At, B0); PG8_MMA(0, 1, At, B1); PG8_BAR; PG8_SCHED;
.LBB0_144:
	ds_read_b128 v[72:75], v170
	ds_read_b128 v[76:79], v170 offset:1024
	ds_read_b128 v[80:83], v170 offset:2048
	ds_read_b128 v[88:91], v170 offset:3072
	ds_read_b128 v[162:165], v171
	ds_read_b128 v[174:177], v171 offset:1024
	ds_read_b128 v[178:181], v171 offset:2048
	ds_read_b128 v[182:185], v171 offset:3072
	s_add_u32 s30, s26, 0xfff80080
	s_addc_u32 s31, s27, -1
	s_cmp_eq_u32 s50, 28
	s_cselect_b32 s35, s7, s31
	s_cselect_b32 s34, s19, s30
	s_cselect_b32 s31, s17, s49
	s_cselect_b32 s30, s36, s37
	s_add_i32 m0, s29, 0xc000
	ds_read_b128 v[192:195], v172
	ds_read_b128 v[196:199], v172 offset:1024
	ds_read_b128 v[200:203], v172 offset:2048
	ds_read_b128 v[204:207], v172 offset:3072
	ds_read_b128 v[208:211], v172 offset:4096
	ds_read_b128 v[212:215], v172 offset:5120
	ds_read_b128 v[216:219], v172 offset:6144
	ds_read_b128 v[220:223], v172 offset:7168
	global_load_lds_dwordx4 v152, s[26:27]
	s_add_i32 m0, s29, 0xe000
	s_nop 0
	global_load_lds_dwordx4 v154, s[26:27]
	s_waitcnt vmcnt(8)
	s_waitcnt lgkmcnt(0)
	s_barrier
	s_setprio 1
	s_waitcnt lgkmcnt(0)
	v_mfma_f32_16x16x32_bf16 v[140:143], v[72:75], v[192:195], v[140:143]
	v_mfma_f32_16x16x32_bf16 v[136:139], v[80:83], v[192:195], v[136:139]
	v_mfma_f32_16x16x32_bf16 v[124:127], v[72:75], v[200:203], v[124:127]
	v_mfma_f32_16x16x32_bf16 v[120:123], v[80:83], v[200:203], v[120:123]
	v_mfma_f32_16x16x32_bf16 v[108:111], v[72:75], v[208:211], v[108:111]
	v_mfma_f32_16x16x32_bf16 v[104:107], v[80:83], v[208:211], v[104:107]
	v_mfma_f32_16x16x32_bf16 v[92:95], v[72:75], v[216:219], v[92:95]
	v_mfma_f32_16x16x32_bf16 v[84:87], v[80:83], v[216:219], v[84:87]
	v_mfma_f32_16x16x32_bf16 v[140:143], v[76:79], v[196:199], v[140:143]
	v_mfma_f32_16x16x32_bf16 v[136:139], v[88:91], v[196:199], v[136:139]
	v_mfma_f32_16x16x32_bf16 v[124:127], v[76:79], v[204:207], v[124:127]
	v_mfma_f32_16x16x32_bf16 v[120:123], v[88:91], v[204:207], v[120:123]
	v_mfma_f32_16x16x32_bf16 v[108:111], v[76:79], v[212:215], v[108:111]
	v_mfma_f32_16x16x32_bf16 v[104:107], v[88:91], v[212:215], v[104:107]
	v_mfma_f32_16x16x32_bf16 v[92:95], v[76:79], v[220:223], v[92:95]
	v_mfma_f32_16x16x32_bf16 v[84:87], v[88:91], v[220:223], v[84:87]
	v_mfma_f32_16x16x32_bf16 v[132:135], v[162:165], v[192:195], v[132:135]
	v_mfma_f32_16x16x32_bf16 v[128:131], v[178:181], v[192:195], v[128:131]
	v_mfma_f32_16x16x32_bf16 v[116:119], v[162:165], v[200:203], v[116:119]
	v_mfma_f32_16x16x32_bf16 v[112:115], v[178:181], v[200:203], v[112:115]
	v_mfma_f32_16x16x32_bf16 v[100:103], v[162:165], v[208:211], v[100:103]
	v_mfma_f32_16x16x32_bf16 v[96:99], v[178:181], v[208:211], v[96:99]
	v_mfma_f32_16x16x32_bf16 v[68:71], v[162:165], v[216:219], v[68:71]
	v_mfma_f32_16x16x32_bf16 v[64:67], v[178:181], v[216:219], v[64:67]
	v_mfma_f32_16x16x32_bf16 v[132:135], v[174:177], v[196:199], v[132:135]
	v_mfma_f32_16x16x32_bf16 v[128:131], v[182:185], v[196:199], v[128:131]
	v_mfma_f32_16x16x32_bf16 v[116:119], v[174:177], v[204:207], v[116:119]
	v_mfma_f32_16x16x32_bf16 v[112:115], v[182:185], v[204:207], v[112:115]
	v_mfma_f32_16x16x32_bf16 v[100:103], v[174:177], v[212:215], v[100:103]
	v_mfma_f32_16x16x32_bf16 v[96:99], v[182:185], v[212:215], v[96:99]
	v_mfma_f32_16x16x32_bf16 v[68:71], v[174:177], v[220:223], v[68:71]
	v_mfma_f32_16x16x32_bf16 v[64:67], v[182:185], v[220:223], v[64:67]
	s_setprio 0
	s_barrier
	s_add_i32 s51, s47, s38
	v_lshl_add_u64 v[166:167], s[30:31], 0, v[146:147]
	s_mov_b32 m0, s51
	ds_read_b128 v[192:195], v172 offset:16384
	ds_read_b128 v[196:199], v172 offset:17408
	ds_read_b128 v[200:203], v172 offset:18432
	ds_read_b128 v[204:207], v172 offset:19456
	ds_read_b128 v[208:211], v172 offset:20480
	ds_read_b128 v[212:215], v172 offset:21504
	ds_read_b128 v[216:219], v172 offset:22528
	ds_read_b128 v[220:223], v172 offset:23552
	global_load_lds_dwordx4 v[166:167], off
	s_add_i32 m0, s51, 0x2000
	s_add_u32 s56, s30, 0x80000
	v_lshl_add_u64 v[188:189], s[30:31], 0, v[150:151]
	s_addc_u32 s57, s31, 0
	s_add_i32 s51, s48, s38
	global_load_lds_dwordx4 v[188:189], off
	s_mov_b32 m0, s51
	v_lshl_add_u64 v[226:227], s[34:35], 0, v[148:149]
	global_load_lds_dwordx4 v146, s[56:57]
	s_add_i32 m0, s51, 0x2000
	s_nop 0
	global_load_lds_dwordx4 v150, s[56:57]
	v_lshl_add_u64 v[224:225], s[34:35], 0, v[144:145]
	s_mov_b32 m0, s29
	s_nop 0
	global_load_lds_dwordx4 v[224:225], off
	s_mov_b32 m0, s39
	s_nop 0
	global_load_lds_dwordx4 v[226:227], off
	s_waitcnt vmcnt(8)
	s_waitcnt lgkmcnt(0)
	s_barrier
	s_setprio 1
	s_waitcnt lgkmcnt(0)
	v_mfma_f32_16x16x32_bf16 v[60:63], v[72:75], v[192:195], v[60:63]
	v_mfma_f32_16x16x32_bf16 v[56:59], v[80:83], v[192:195], v[56:59]
	v_mfma_f32_16x16x32_bf16 v[44:47], v[72:75], v[200:203], v[44:47]
	v_mfma_f32_16x16x32_bf16 v[40:43], v[80:83], v[200:203], v[40:43]
	v_mfma_f32_16x16x32_bf16 v[28:31], v[72:75], v[208:211], v[28:31]
	v_mfma_f32_16x16x32_bf16 v[24:27], v[80:83], v[208:211], v[24:27]
	v_mfma_f32_16x16x32_bf16 v[12:15], v[72:75], v[216:219], v[12:15]
	v_mfma_f32_16x16x32_bf16 v[8:11], v[80:83], v[216:219], v[8:11]
	v_mfma_f32_16x16x32_bf16 v[60:63], v[76:79], v[196:199], v[60:63]
	v_mfma_f32_16x16x32_bf16 v[56:59], v[88:91], v[196:199], v[56:59]
	v_mfma_f32_16x16x32_bf16 v[44:47], v[76:79], v[204:207], v[44:47]
	v_mfma_f32_16x16x32_bf16 v[40:43], v[88:91], v[204:207], v[40:43]
	v_mfma_f32_16x16x32_bf16 v[28:31], v[76:79], v[212:215], v[28:31]
	v_mfma_f32_16x16x32_bf16 v[24:27], v[88:91], v[212:215], v[24:27]
	v_mfma_f32_16x16x32_bf16 v[12:15], v[76:79], v[220:223], v[12:15]
	v_mfma_f32_16x16x32_bf16 v[8:11], v[88:91], v[220:223], v[8:11]
	v_mfma_f32_16x16x32_bf16 v[52:55], v[162:165], v[192:195], v[52:55]
	v_mfma_f32_16x16x32_bf16 v[48:51], v[178:181], v[192:195], v[48:51]
	v_mfma_f32_16x16x32_bf16 v[36:39], v[162:165], v[200:203], v[36:39]
	v_mfma_f32_16x16x32_bf16 v[32:35], v[178:181], v[200:203], v[32:35]
	v_mfma_f32_16x16x32_bf16 v[20:23], v[162:165], v[208:211], v[20:23]
	v_mfma_f32_16x16x32_bf16 v[16:19], v[178:181], v[208:211], v[16:19]
	v_mfma_f32_16x16x32_bf16 v[4:7], v[162:165], v[216:219], v[4:7]
	v_mfma_f32_16x16x32_bf16 v[0:3], v[178:181], v[216:219], v[0:3]
	v_mfma_f32_16x16x32_bf16 v[52:55], v[174:177], v[196:199], v[52:55]
	v_mfma_f32_16x16x32_bf16 v[48:51], v[182:185], v[196:199], v[48:51]
	v_mfma_f32_16x16x32_bf16 v[36:39], v[174:177], v[204:207], v[36:39]
	v_mfma_f32_16x16x32_bf16 v[32:35], v[182:185], v[204:207], v[32:35]
	v_mfma_f32_16x16x32_bf16 v[20:23], v[174:177], v[212:215], v[20:23]
	v_mfma_f32_16x16x32_bf16 v[16:19], v[182:185], v[212:215], v[16:19]
	v_mfma_f32_16x16x32_bf16 v[4:7], v[174:177], v[220:223], v[4:7]
	v_mfma_f32_16x16x32_bf16 v[0:3], v[182:185], v[220:223], v[0:3]
	s_setprio 0
	s_barrier
; #define PG8_STAGE(bufoff, gbase, voff) do { _Pragma("unroll") for (int _i = 0; _i < 2; ++_i) \
;         __builtin_amdgcn_global_load_lds((const unsigned*)((const char*)(gbase) + (voff)[_i]), (LAS unsigned*)(lds + (bufoff) + ldsw + _i * 8192), 16, 0, 0); } while (0)
; #define PG8_LDA(dst, b, h) do { _Pragma("unroll") for (int m = 0; m < 4; ++m) _Pragma("unroll") for (int k = 0; k < 2; ++k) dst[m][k] = *(const LAS bf16x8*)(lds + PG8_SA(b, h) + aoff + m * 2048 + k * 1024); } while (0)
; #define PG8_WAIT_V(n) asm volatile("s_waitcnt vmcnt(" #n ")" ::: "memory")
; #define PG8_WAIT_L(n) asm volatile("s_waitcnt lgkmcnt(" #n ")" ::: "memory")
; #define PG8_BAR __builtin_amdgcn_s_barrier()
; #define PG8_SCHED __builtin_amdgcn_sched_barrier(0)
; template <class Epi, class Sched, bool F8 = false>
; __device__ __forceinline__ void gemm_phase(LAS unsigned char* lds, const Gemm g, const Sched& S, const Epi& E) {
;     ...
;             PG8_WAIT_V(8); PG8_WAIT_L(0); PG8_BAR; PG8_MMA(0, 0, At, B0); PG8_MMA(0, 1, At, B1); PG8_BAR; PG8_SCHED;
;             PG8_LDA(At, 1, 1); PG8_STAGE(PG8_SB(1, 0), b3, voffB); PG8_STAGE(PG8_SB(1, 1), b3 + hstepB, voffB); PG8_STAGE(PG8_SA(1, 0), a3, voffA);
;             PG8_WAIT_V(8); PG8_WAIT_L(0); PG8_BAR; PG8_MMA(1, 0, At, B0); PG8_MMA(1, 1, At, B1); PG8_BAR; PG8_SCHED;
;         }
;         if (wr == 0) PG8_BAR;
	s_add_i32 s51, 0, 0x18000
	s_add_i32 s53, 0, 0x1c000
	v_add_u32_e32 v88, s51, v168
	v_add_u32_e32 v173, s53, v168
	ds_read_b128 v[72:75], v88
	ds_read_b128 v[76:79], v88 offset:1024
	ds_read_b128 v[80:83], v88 offset:2048
	ds_read_b128 v[88:91], v88 offset:3072
	ds_read_b128 v[162:165], v173
	ds_read_b128 v[174:177], v173 offset:1024
	ds_read_b128 v[178:181], v173 offset:2048
	ds_read_b128 v[182:185], v173 offset:3072
	s_add_u32 s34, s34, 0x80000
	s_addc_u32 s35, s35, 0
	s_mov_b32 m0, s40
	ds_read_b128 v[192:195], v172 offset:32768
	ds_read_b128 v[196:199], v172 offset:33792
	ds_read_b128 v[200:203], v172 offset:34816
	ds_read_b128 v[204:207], v172 offset:35840
	ds_read_b128 v[208:211], v172 offset:36864
	ds_read_b128 v[212:215], v172 offset:37888
	ds_read_b128 v[216:219], v172 offset:38912
	ds_read_b128 v[220:223], v172 offset:39936
	global_load_lds_dwordx4 v144, s[34:35]
	s_mov_b32 m0, s41
	s_nop 0
	global_load_lds_dwordx4 v148, s[34:35]
	s_waitcnt vmcnt(8)
	s_waitcnt lgkmcnt(0)
	s_barrier
	s_setprio 1
	s_waitcnt lgkmcnt(0)
	v_mfma_f32_16x16x32_bf16 v[140:143], v[72:75], v[192:195], v[140:143]
	v_mfma_f32_16x16x32_bf16 v[136:139], v[80:83], v[192:195], v[136:139]
	v_mfma_f32_16x16x32_bf16 v[124:127], v[72:75], v[200:203], v[124:127]
	v_mfma_f32_16x16x32_bf16 v[120:123], v[80:83], v[200:203], v[120:123]
	v_mfma_f32_16x16x32_bf16 v[108:111], v[72:75], v[208:211], v[108:111]
	v_mfma_f32_16x16x32_bf16 v[104:107], v[80:83], v[208:211], v[104:107]
	v_mfma_f32_16x16x32_bf16 v[92:95], v[72:75], v[216:219], v[92:95]
	v_mfma_f32_16x16x32_bf16 v[84:87], v[80:83], v[216:219], v[84:87]
	v_mfma_f32_16x16x32_bf16 v[140:143], v[76:79], v[196:199], v[140:143]
	v_mfma_f32_16x16x32_bf16 v[136:139], v[88:91], v[196:199], v[136:139]
	v_mfma_f32_16x16x32_bf16 v[124:127], v[76:79], v[204:207], v[124:127]
	v_mfma_f32_16x16x32_bf16 v[120:123], v[88:91], v[204:207], v[120:123]
	v_mfma_f32_16x16x32_bf16 v[108:111], v[76:79], v[212:215], v[108:111]
	v_mfma_f32_16x16x32_bf16 v[104:107], v[88:91], v[212:215], v[104:107]
	v_mfma_f32_16x16x32_bf16 v[92:95], v[76:79], v[220:223], v[92:95]
	v_mfma_f32_16x16x32_bf16 v[84:87], v[88:91], v[220:223], v[84:87]
	v_mfma_f32_16x16x32_bf16 v[132:135], v[162:165], v[192:195], v[132:135]
	v_mfma_f32_16x16x32_bf16 v[128:131], v[178:181], v[192:195], v[128:131]
	v_mfma_f32_16x16x32_bf16 v[116:119], v[162:165], v[200:203], v[116:119]
	v_mfma_f32_16x16x32_bf16 v[112:115], v[178:181], v[200:203], v[112:115]
	v_mfma_f32_16x16x32_bf16 v[100:103], v[162:165], v[208:211], v[100:103]
	v_mfma_f32_16x16x32_bf16 v[96:99], v[178:181], v[208:211], v[96:99]
	v_mfma_f32_16x16x32_bf16 v[68:71], v[162:165], v[216:219], v[68:71]
	v_mfma_f32_16x16x32_bf16 v[64:67], v[178:181], v[216:219], v[64:67]
	v_mfma_f32_16x16x32_bf16 v[132:135], v[174:177], v[196:199], v[132:135]
	v_mfma_f32_16x16x32_bf16 v[128:131], v[182:185], v[196:199], v[128:131]
	v_mfma_f32_16x16x32_bf16 v[116:119], v[174:177], v[204:207], v[116:119]
	v_mfma_f32_16x16x32_bf16 v[112:115], v[182:185], v[204:207], v[112:115]
	v_mfma_f32_16x16x32_bf16 v[100:103], v[174:177], v[212:215], v[100:103]
	v_mfma_f32_16x16x32_bf16 v[96:99], v[182:185], v[212:215], v[96:99]
	v_mfma_f32_16x16x32_bf16 v[68:71], v[174:177], v[220:223], v[68:71]
	v_mfma_f32_16x16x32_bf16 v[64:67], v[182:185], v[220:223], v[64:67]
	s_setprio 0
	s_barrier
	s_add_i32 s34, s51, s38
	s_add_i32 m0, s34, 0xffffff80
	ds_read_b128 v[192:195], v172 offset:49152
	ds_read_b128 v[196:199], v172 offset:50176
	ds_read_b128 v[200:203], v172 offset:51200
	ds_read_b128 v[204:207], v172 offset:52224
	ds_read_b128 v[208:211], v172 offset:53248
	ds_read_b128 v[212:215], v172 offset:54272
	ds_read_b128 v[216:219], v172 offset:55296
	ds_read_b128 v[220:223], v172 offset:56320
	global_load_lds_dwordx4 v[166:167], off offset:128
	s_add_i32 m0, s34, 0x1f80
	s_add_u32 s30, s30, 0x80080
	s_addc_u32 s31, s31, 0
	s_add_i32 s34, s53, s38
	global_load_lds_dwordx4 v[188:189], off offset:128
	s_mov_b32 m0, s34
	s_nop 0
	global_load_lds_dwordx4 v146, s[30:31]
	s_add_i32 m0, s34, 0x2000
	s_nop 0
	global_load_lds_dwordx4 v150, s[30:31]
	s_add_i32 m0, s43, 0xffffff80
	s_nop 0
	global_load_lds_dwordx4 v[224:225], off offset:128
	s_add_i32 m0, s44, 0xffffff80
	s_nop 0
	global_load_lds_dwordx4 v[226:227], off offset:128
	s_waitcnt vmcnt(8)
	s_waitcnt lgkmcnt(0)
	s_barrier
	s_setprio 1
	s_waitcnt lgkmcnt(0)
	v_mfma_f32_16x16x32_bf16 v[60:63], v[72:75], v[192:195], v[60:63]
	v_mfma_f32_16x16x32_bf16 v[56:59], v[80:83], v[192:195], v[56:59]
	v_mfma_f32_16x16x32_bf16 v[44:47], v[72:75], v[200:203], v[44:47]
	v_mfma_f32_16x16x32_bf16 v[40:43], v[80:83], v[200:203], v[40:43]
	v_mfma_f32_16x16x32_bf16 v[28:31], v[72:75], v[208:211], v[28:31]
	v_mfma_f32_16x16x32_bf16 v[24:27], v[80:83], v[208:211], v[24:27]
	v_mfma_f32_16x16x32_bf16 v[12:15], v[72:75], v[216:219], v[12:15]
	v_mfma_f32_16x16x32_bf16 v[8:11], v[80:83], v[216:219], v[8:11]
	v_mfma_f32_16x16x32_bf16 v[60:63], v[76:79], v[196:199], v[60:63]
	v_mfma_f32_16x16x32_bf16 v[56:59], v[88:91], v[196:199], v[56:59]
	v_mfma_f32_16x16x32_bf16 v[44:47], v[76:79], v[204:207], v[44:47]
	v_mfma_f32_16x16x32_bf16 v[40:43], v[88:91], v[204:207], v[40:43]
	v_mfma_f32_16x16x32_bf16 v[28:31], v[76:79], v[212:215], v[28:31]
	v_mfma_f32_16x16x32_bf16 v[24:27], v[88:91], v[212:215], v[24:27]
	v_mfma_f32_16x16x32_bf16 v[12:15], v[76:79], v[220:223], v[12:15]
	v_mfma_f32_16x16x32_bf16 v[8:11], v[88:91], v[220:223], v[8:11]
	v_mfma_f32_16x16x32_bf16 v[52:55], v[162:165], v[192:195], v[52:55]
	v_mfma_f32_16x16x32_bf16 v[48:51], v[178:181], v[192:195], v[48:51]
	v_mfma_f32_16x16x32_bf16 v[36:39], v[162:165], v[200:203], v[36:39]
	v_mfma_f32_16x16x32_bf16 v[32:35], v[178:181], v[200:203], v[32:35]
	v_mfma_f32_16x16x32_bf16 v[20:23], v[162:165], v[208:211], v[20:23]
	v_mfma_f32_16x16x32_bf16 v[16:19], v[178:181], v[208:211], v[16:19]
	v_mfma_f32_16x16x32_bf16 v[4:7], v[162:165], v[216:219], v[4:7]
	v_mfma_f32_16x16x32_bf16 v[0:3], v[178:181], v[216:219], v[0:3]
	v_mfma_f32_16x16x32_bf16 v[52:55], v[174:177], v[196:199], v[52:55]
	v_mfma_f32_16x16x32_bf16 v[48:51], v[182:185], v[196:199], v[48:51]
	v_mfma_f32_16x16x32_bf16 v[36:39], v[174:177], v[204:207], v[36:39]
	v_mfma_f32_16x16x32_bf16 v[32:35], v[182:185], v[204:207], v[32:35]
	v_mfma_f32_16x16x32_bf16 v[20:23], v[174:177], v[212:215], v[20:23]
	v_mfma_f32_16x16x32_bf16 v[16:19], v[182:185], v[212:215], v[16:19]
	v_mfma_f32_16x16x32_bf16 v[4:7], v[174:177], v[220:223], v[4:7]
	v_mfma_f32_16x16x32_bf16 v[0:3], v[182:185], v[220:223], v[0:3]
	s_setprio 0
	s_barrier
	s_add_i32 s50, s50, 2
	s_add_u32 s26, s26, 0x100
	s_addc_u32 s27, s27, 0
	s_add_u32 s37, s37, 0x100
	s_addc_u32 s49, s49, 0
	s_cmp_gt_u32 s50, 29
	s_cbranch_scc0 .LBB0_144
	s_and_b64 vcc, exec, s[14:15]
	s_cbranch_vccz .LBB0_147
	s_barrier

; #define PG8_STAGE(bufoff, gbase, voff) do { _Pragma("unroll") for (int _i = 0; _i < 2; ++_i) \
;         __builtin_amdgcn_global_load_lds((const unsigned*)((const char*)(gbase) + (voff)[_i]), (LAS unsigned*)(lds + (bufoff) + ldsw + _i * 8192), 16, 0, 0); } while (0)
; #define PG8_LDA(dst, b, h) do { _Pragma("unroll") for (int m = 0; m < 4; ++m) _Pragma("unroll") for (int k = 0; k < 2; ++k) dst[m][k] = *(const LAS bf16x8*)(lds + PG8_SA(b, h) + aoff + m * 2048 + k * 1024); } while (0)
; #define PG8_LDB(dst, b, h) do { _Pragma("unroll") for (int n = 0; n < 2; ++n) _Pragma("unroll") for (int k = 0; k < 2; ++k) dst[n][k] = *(const LAS bf16x8*)(lds + PG8_SB(b, h) + boff + n * 2048 + k * 1024); } while (0)
; #define PG8_WAIT_V(n) asm volatile("s_waitcnt vmcnt(" #n ")" ::: "memory")
; #define PG8_WAIT_L(n) asm volatile("s_waitcnt lgkmcnt(" #n ")" ::: "memory")
; #define PG8_BAR __builtin_amdgcn_s_barrier()
; #define PG8_SCHED __builtin_amdgcn_sched_barrier(0)
; template <class Epi, class Sched, bool F8 = false>
; __device__ __forceinline__ void gemm_phase(LAS unsigned char* lds, const Gemm g, const Sched& S, const Epi& E) {
;     ...
;             const bool last = (t == nt - 2);
;             const char* a1 = cA + (size_t)(t + 1) * kstep;
;             const char* a2 = last ? nA : cA + (size_t)(t + 2) * kstep; const char* b2 = last ? nB : cB + (size_t)(t + 2) * kstep;
;             const char* a3 = a2 + kstep; const char* b3 = b2 + kstep;
;             PG8_LDB(B0, 0, 0); PG8_LDB(B1, 0, 1); PG8_SCHED; PG8_LDA(At, 0, 0); PG8_STAGE(PG8_SA(1, 1), a1 + hstepA, voffA);
;             PG8_WAIT_V(8); PG8_WAIT_L(0); PG8_BAR; PG8_MMA(0, 0, At, B0); PG8_MMA(0, 1, At, B1); PG8_BAR; PG8_SCHED;
;             PG8_LDA(At, 0, 1); PG8_STAGE(PG8_SB(0, 0), b2, voffB); PG8_STAGE(PG8_SB(0, 1), b2 + hstepB, voffB); PG8_STAGE(PG8_SA(0, 0), a2, voffA);
;             PG8_WAIT_V(8); PG8_WAIT_L(0); PG8_BAR; PG8_MMA(1, 0, At, B0); PG8_MMA(1, 1, At, B1); PG8_BAR; PG8_SCHED;
;             PG8_LDB(B0, 1, 0); PG8_LDB(B1, 1, 1); PG8_SCHED; PG8_LDA(At, 1, 0); PG8_STAGE(PG8_SA(0, 1), a2 + hstepA, voffA);
;             PG8_WAIT_V(8); PG8_WAIT_L(0); PG8_BAR; PG8_MMA(0, 0, At, B0); PG8_MMA(0, 1, At, B1); PG8_BAR; PG8_SCHED;
.LBB0_208:
	ds_read_b128 v[152:155], v189
	ds_read_b128 v[156:159], v189 offset:1024
	ds_read_b128 v[144:147], v189 offset:2048
	ds_read_b128 v[148:151], v189 offset:3072
	ds_read_b128 v[136:139], v191
	ds_read_b128 v[140:143], v191 offset:1024
	ds_read_b128 v[128:131], v191 offset:2048
	ds_read_b128 v[132:135], v191 offset:3072
	s_add_u32 s30, s28, 0xfffc0080
	s_addc_u32 s31, s29, -1
	s_cmp_eq_u32 s53, 12
	s_cselect_b32 s35, s21, s31
	s_cselect_b32 s34, s48, s30
	s_cselect_b32 s31, s19, s51
	s_cselect_b32 s30, s49, s50
	s_add_i32 m0, s27, 0xc000
	ds_read_b128 v[178:181], v192
	ds_read_b128 v[182:185], v192 offset:1024
	ds_read_b128 v[194:197], v192 offset:2048
	ds_read_b128 v[198:201], v192 offset:3072
	ds_read_b128 v[202:205], v192 offset:4096
	ds_read_b128 v[206:209], v192 offset:5120
	ds_read_b128 v[210:213], v192 offset:6144
	ds_read_b128 v[214:217], v192 offset:7168
	global_load_lds_dwordx4 v170, s[28:29]
	s_add_i32 m0, s27, 0xe000
	s_nop 0
	global_load_lds_dwordx4 v172, s[28:29]
	s_waitcnt vmcnt(8)
	s_waitcnt lgkmcnt(0)
	s_barrier
	s_setprio 1
	s_waitcnt lgkmcnt(0)
	v_mfma_scale_f32_16x16x128_f8f6f4 v[124:127], v[152:159], v[178:185], v[124:127], v254, v254 op_sel_hi:[0,0,0]
	v_mfma_scale_f32_16x16x128_f8f6f4 v[120:123], v[144:151], v[178:185], v[120:123], v254, v254 op_sel_hi:[0,0,0]
	v_mfma_scale_f32_16x16x128_f8f6f4 v[108:111], v[152:159], v[194:201], v[108:111], v254, v254 op_sel_hi:[0,0,0]
	v_mfma_scale_f32_16x16x128_f8f6f4 v[104:107], v[144:151], v[194:201], v[104:107], v254, v254 op_sel_hi:[0,0,0]
	v_mfma_scale_f32_16x16x128_f8f6f4 v[92:95], v[152:159], v[202:209], v[92:95], v254, v254 op_sel_hi:[0,0,0]
	v_mfma_scale_f32_16x16x128_f8f6f4 v[88:91], v[144:151], v[202:209], v[88:91], v254, v254 op_sel_hi:[0,0,0]
	v_mfma_scale_f32_16x16x128_f8f6f4 v[76:79], v[152:159], v[210:217], v[76:79], v254, v254 op_sel_hi:[0,0,0]
	v_mfma_scale_f32_16x16x128_f8f6f4 v[72:75], v[144:151], v[210:217], v[72:75], v254, v254 op_sel_hi:[0,0,0]
	v_mfma_scale_f32_16x16x128_f8f6f4 v[116:119], v[136:143], v[178:185], v[116:119], v254, v254 op_sel_hi:[0,0,0]
	v_mfma_scale_f32_16x16x128_f8f6f4 v[112:115], v[128:135], v[178:185], v[112:115], v254, v254 op_sel_hi:[0,0,0]
	v_mfma_scale_f32_16x16x128_f8f6f4 v[100:103], v[136:143], v[194:201], v[100:103], v254, v254 op_sel_hi:[0,0,0]
	v_mfma_scale_f32_16x16x128_f8f6f4 v[96:99], v[128:135], v[194:201], v[96:99], v254, v254 op_sel_hi:[0,0,0]
	v_mfma_scale_f32_16x16x128_f8f6f4 v[84:87], v[136:143], v[202:209], v[84:87], v254, v254 op_sel_hi:[0,0,0]
	v_mfma_scale_f32_16x16x128_f8f6f4 v[80:83], v[128:135], v[202:209], v[80:83], v254, v254 op_sel_hi:[0,0,0]
	v_mfma_scale_f32_16x16x128_f8f6f4 v[68:71], v[136:143], v[210:217], v[68:71], v254, v254 op_sel_hi:[0,0,0]
	v_mfma_scale_f32_16x16x128_f8f6f4 v[64:67], v[128:135], v[210:217], v[64:67], v254, v254 op_sel_hi:[0,0,0]
	s_setprio 0
	s_barrier
	s_add_i32 s56, s43, s17
	v_lshl_add_u64 v[178:179], s[30:31], 0, v[166:167]
	s_mov_b32 m0, s56
	ds_read_b128 v[194:197], v192 offset:16384
	ds_read_b128 v[198:201], v192 offset:17408
	ds_read_b128 v[202:205], v192 offset:18432
	ds_read_b128 v[206:209], v192 offset:19456
	ds_read_b128 v[210:213], v192 offset:20480
	ds_read_b128 v[214:217], v192 offset:21504
	ds_read_b128 v[218:221], v192 offset:22528
	ds_read_b128 v[222:225], v192 offset:23552
	global_load_lds_dwordx4 v[178:179], off
	s_add_i32 m0, s56, 0x2000
	s_add_u32 s56, s30, 0x40000
	v_lshl_add_u64 v[180:181], s[30:31], 0, v[162:163]
	s_addc_u32 s57, s31, 0
	s_add_i32 s58, s44, s17
	global_load_lds_dwordx4 v[180:181], off
	s_mov_b32 m0, s58
	v_lshl_add_u64 v[184:185], s[34:35], 0, v[164:165]
	global_load_lds_dwordx4 v166, s[56:57]
	s_add_i32 m0, s58, 0x2000
	s_nop 0
	global_load_lds_dwordx4 v162, s[56:57]
	v_lshl_add_u64 v[182:183], s[34:35], 0, v[168:169]
	s_mov_b32 m0, s27
	s_nop 0
	global_load_lds_dwordx4 v[182:183], off
	s_mov_b32 m0, s37
	s_nop 0
	global_load_lds_dwordx4 v[184:185], off
	s_waitcnt vmcnt(8)
	s_waitcnt lgkmcnt(0)
	s_barrier
	s_setprio 1
	s_waitcnt lgkmcnt(0)
	v_mfma_scale_f32_16x16x128_f8f6f4 v[60:63], v[152:159], v[194:201], v[60:63], v254, v254 op_sel_hi:[0,0,0]
	v_mfma_scale_f32_16x16x128_f8f6f4 v[56:59], v[144:151], v[194:201], v[56:59], v254, v254 op_sel_hi:[0,0,0]
	v_mfma_scale_f32_16x16x128_f8f6f4 v[44:47], v[152:159], v[202:209], v[44:47], v254, v254 op_sel_hi:[0,0,0]
	v_mfma_scale_f32_16x16x128_f8f6f4 v[40:43], v[144:151], v[202:209], v[40:43], v254, v254 op_sel_hi:[0,0,0]
	v_mfma_scale_f32_16x16x128_f8f6f4 v[28:31], v[152:159], v[210:217], v[28:31], v254, v254 op_sel_hi:[0,0,0]
	v_mfma_scale_f32_16x16x128_f8f6f4 v[24:27], v[144:151], v[210:217], v[24:27], v254, v254 op_sel_hi:[0,0,0]
	v_mfma_scale_f32_16x16x128_f8f6f4 v[12:15], v[152:159], v[218:225], v[12:15], v254, v254 op_sel_hi:[0,0,0]
	v_mfma_scale_f32_16x16x128_f8f6f4 v[8:11], v[144:151], v[218:225], v[8:11], v254, v254 op_sel_hi:[0,0,0]
	v_mfma_scale_f32_16x16x128_f8f6f4 v[52:55], v[136:143], v[194:201], v[52:55], v254, v254 op_sel_hi:[0,0,0]
	v_mfma_scale_f32_16x16x128_f8f6f4 v[48:51], v[128:135], v[194:201], v[48:51], v254, v254 op_sel_hi:[0,0,0]
	v_mfma_scale_f32_16x16x128_f8f6f4 v[36:39], v[136:143], v[202:209], v[36:39], v254, v254 op_sel_hi:[0,0,0]
	v_mfma_scale_f32_16x16x128_f8f6f4 v[32:35], v[128:135], v[202:209], v[32:35], v254, v254 op_sel_hi:[0,0,0]
	v_mfma_scale_f32_16x16x128_f8f6f4 v[20:23], v[136:143], v[210:217], v[20:23], v254, v254 op_sel_hi:[0,0,0]
	v_mfma_scale_f32_16x16x128_f8f6f4 v[16:19], v[128:135], v[210:217], v[16:19], v254, v254 op_sel_hi:[0,0,0]
	v_mfma_scale_f32_16x16x128_f8f6f4 v[4:7], v[136:143], v[218:225], v[4:7], v254, v254 op_sel_hi:[0,0,0]
	v_mfma_scale_f32_16x16x128_f8f6f4 v[0:3], v[128:135], v[218:225], v[0:3], v254, v254 op_sel_hi:[0,0,0]
	s_setprio 0
	s_barrier
; #define PG8_STAGE(bufoff, gbase, voff) do { _Pragma("unroll") for (int _i = 0; _i < 2; ++_i) \
;         __builtin_amdgcn_global_load_lds((const unsigned*)((const char*)(gbase) + (voff)[_i]), (LAS unsigned*)(lds + (bufoff) + ldsw + _i * 8192), 16, 0, 0); } while (0)
; #define PG8_LDA(dst, b, h) do { _Pragma("unroll") for (int m = 0; m < 4; ++m) _Pragma("unroll") for (int k = 0; k < 2; ++k) dst[m][k] = *(const LAS bf16x8*)(lds + PG8_SA(b, h) + aoff + m * 2048 + k * 1024); } while (0)
; #define PG8_WAIT_V(n) asm volatile("s_waitcnt vmcnt(" #n ")" ::: "memory")
; #define PG8_WAIT_L(n) asm volatile("s_waitcnt lgkmcnt(" #n ")" ::: "memory")
; #define PG8_BAR __builtin_amdgcn_s_barrier()
; #define PG8_SCHED __builtin_amdgcn_sched_barrier(0)
; template <class Epi, class Sched, bool F8 = false>
; __device__ __forceinline__ void gemm_phase(LAS unsigned char* lds, const Gemm g, const Sched& S, const Epi& E) {
;     ...
;             PG8_WAIT_V(8); PG8_WAIT_L(0); PG8_BAR; PG8_MMA(0, 0, At, B0); PG8_MMA(0, 1, At, B1); PG8_BAR; PG8_SCHED;
;             PG8_LDA(At, 1, 1); PG8_STAGE(PG8_SB(1, 0), b3, voffB); PG8_STAGE(PG8_SB(1, 1), b3 + hstepB, voffB); PG8_STAGE(PG8_SA(1, 0), a3, voffA);
;             PG8_WAIT_V(8); PG8_WAIT_L(0); PG8_BAR; PG8_MMA(1, 0, At, B0); PG8_MMA(1, 1, At, B1); PG8_BAR; PG8_SCHED;
;         }
;         if (wr == 0) PG8_BAR;
	s_add_i32 s56, 0, 0x18000
	v_add_u32_e32 v128, s56, v187
	s_add_i32 s57, 0, 0x1c000
	ds_read_b128 v[152:155], v128
	ds_read_b128 v[156:159], v128 offset:1024
	ds_read_b128 v[144:147], v128 offset:2048
	ds_read_b128 v[148:151], v128 offset:3072
	v_add_u32_e32 v128, s57, v187
	ds_read_b128 v[136:139], v128
	ds_read_b128 v[140:143], v128 offset:1024
	ds_read_b128 v[132:135], v128 offset:3072
	ds_read_b128 v[128:131], v128 offset:2048
	s_add_u32 s34, s34, 0x40000
	s_addc_u32 s35, s35, 0
	s_mov_b32 m0, s38
	ds_read_b128 v[194:197], v192 offset:32768
	ds_read_b128 v[198:201], v192 offset:33792
	ds_read_b128 v[202:205], v192 offset:34816
	ds_read_b128 v[206:209], v192 offset:35840
	ds_read_b128 v[210:213], v192 offset:36864
	ds_read_b128 v[214:217], v192 offset:37888
	ds_read_b128 v[218:221], v192 offset:38912
	ds_read_b128 v[222:225], v192 offset:39936
	global_load_lds_dwordx4 v168, s[34:35]
	s_mov_b32 m0, s39
	s_nop 0
	global_load_lds_dwordx4 v164, s[34:35]
	s_waitcnt vmcnt(8)
	s_waitcnt lgkmcnt(0)
	s_barrier
	s_setprio 1
	s_waitcnt lgkmcnt(0)
	v_mfma_scale_f32_16x16x128_f8f6f4 v[124:127], v[152:159], v[194:201], v[124:127], v254, v254 op_sel_hi:[0,0,0]
	v_mfma_scale_f32_16x16x128_f8f6f4 v[120:123], v[144:151], v[194:201], v[120:123], v254, v254 op_sel_hi:[0,0,0]
	v_mfma_scale_f32_16x16x128_f8f6f4 v[108:111], v[152:159], v[202:209], v[108:111], v254, v254 op_sel_hi:[0,0,0]
	v_mfma_scale_f32_16x16x128_f8f6f4 v[104:107], v[144:151], v[202:209], v[104:107], v254, v254 op_sel_hi:[0,0,0]
	v_mfma_scale_f32_16x16x128_f8f6f4 v[92:95], v[152:159], v[210:217], v[92:95], v254, v254 op_sel_hi:[0,0,0]
	v_mfma_scale_f32_16x16x128_f8f6f4 v[88:91], v[144:151], v[210:217], v[88:91], v254, v254 op_sel_hi:[0,0,0]
	v_mfma_scale_f32_16x16x128_f8f6f4 v[76:79], v[152:159], v[218:225], v[76:79], v254, v254 op_sel_hi:[0,0,0]
	v_mfma_scale_f32_16x16x128_f8f6f4 v[72:75], v[144:151], v[218:225], v[72:75], v254, v254 op_sel_hi:[0,0,0]
	v_mfma_scale_f32_16x16x128_f8f6f4 v[116:119], v[136:143], v[194:201], v[116:119], v254, v254 op_sel_hi:[0,0,0]
	v_mfma_scale_f32_16x16x128_f8f6f4 v[112:115], v[128:135], v[194:201], v[112:115], v254, v254 op_sel_hi:[0,0,0]
	v_mfma_scale_f32_16x16x128_f8f6f4 v[100:103], v[136:143], v[202:209], v[100:103], v254, v254 op_sel_hi:[0,0,0]
	v_mfma_scale_f32_16x16x128_f8f6f4 v[96:99], v[128:135], v[202:209], v[96:99], v254, v254 op_sel_hi:[0,0,0]
	v_mfma_scale_f32_16x16x128_f8f6f4 v[84:87], v[136:143], v[210:217], v[84:87], v254, v254 op_sel_hi:[0,0,0]
	v_mfma_scale_f32_16x16x128_f8f6f4 v[80:83], v[128:135], v[210:217], v[80:83], v254, v254 op_sel_hi:[0,0,0]
	v_mfma_scale_f32_16x16x128_f8f6f4 v[68:71], v[136:143], v[218:225], v[68:71], v254, v254 op_sel_hi:[0,0,0]
	v_mfma_scale_f32_16x16x128_f8f6f4 v[64:67], v[128:135], v[218:225], v[64:67], v254, v254 op_sel_hi:[0,0,0]
	s_setprio 0
	s_barrier
	s_add_i32 s34, s56, s17
	s_add_i32 m0, s34, 0xffffff80
	ds_read_b128 v[194:197], v192 offset:49152
	ds_read_b128 v[198:201], v192 offset:50176
	ds_read_b128 v[202:205], v192 offset:51200
	ds_read_b128 v[206:209], v192 offset:52224
	ds_read_b128 v[210:213], v192 offset:53248
	ds_read_b128 v[214:217], v192 offset:54272
	ds_read_b128 v[218:221], v192 offset:55296
	ds_read_b128 v[222:225], v192 offset:56320
	global_load_lds_dwordx4 v[178:179], off offset:128
	s_add_i32 m0, s34, 0x1f80
	s_add_u32 s30, s30, 0x40080
	s_addc_u32 s31, s31, 0
	s_add_i32 s34, s57, s17
	global_load_lds_dwordx4 v[180:181], off offset:128
	s_mov_b32 m0, s34
	s_nop 0
	global_load_lds_dwordx4 v166, s[30:31]
	s_add_i32 m0, s34, 0x2000
	s_nop 0
	global_load_lds_dwordx4 v162, s[30:31]
	s_add_i32 m0, s41, 0xffffff80
	s_nop 0
	global_load_lds_dwordx4 v[182:183], off offset:128
	s_add_i32 m0, s42, 0xffffff80
	s_nop 0
	global_load_lds_dwordx4 v[184:185], off offset:128
	s_waitcnt vmcnt(8)
	s_waitcnt lgkmcnt(0)
	s_barrier
	s_setprio 1
	s_waitcnt lgkmcnt(0)
	v_mfma_scale_f32_16x16x128_f8f6f4 v[60:63], v[152:159], v[194:201], v[60:63], v254, v254 op_sel_hi:[0,0,0]
	v_mfma_scale_f32_16x16x128_f8f6f4 v[56:59], v[144:151], v[194:201], v[56:59], v254, v254 op_sel_hi:[0,0,0]
	v_mfma_scale_f32_16x16x128_f8f6f4 v[44:47], v[152:159], v[202:209], v[44:47], v254, v254 op_sel_hi:[0,0,0]
	v_mfma_scale_f32_16x16x128_f8f6f4 v[40:43], v[144:151], v[202:209], v[40:43], v254, v254 op_sel_hi:[0,0,0]
	v_mfma_scale_f32_16x16x128_f8f6f4 v[28:31], v[152:159], v[210:217], v[28:31], v254, v254 op_sel_hi:[0,0,0]
	v_mfma_scale_f32_16x16x128_f8f6f4 v[24:27], v[144:151], v[210:217], v[24:27], v254, v254 op_sel_hi:[0,0,0]
	v_mfma_scale_f32_16x16x128_f8f6f4 v[12:15], v[152:159], v[218:225], v[12:15], v254, v254 op_sel_hi:[0,0,0]
	v_mfma_scale_f32_16x16x128_f8f6f4 v[8:11], v[144:151], v[218:225], v[8:11], v254, v254 op_sel_hi:[0,0,0]
	v_mfma_scale_f32_16x16x128_f8f6f4 v[52:55], v[136:143], v[194:201], v[52:55], v254, v254 op_sel_hi:[0,0,0]
	v_mfma_scale_f32_16x16x128_f8f6f4 v[48:51], v[128:135], v[194:201], v[48:51], v254, v254 op_sel_hi:[0,0,0]
	v_mfma_scale_f32_16x16x128_f8f6f4 v[36:39], v[136:143], v[202:209], v[36:39], v254, v254 op_sel_hi:[0,0,0]
	v_mfma_scale_f32_16x16x128_f8f6f4 v[32:35], v[128:135], v[202:209], v[32:35], v254, v254 op_sel_hi:[0,0,0]
	v_mfma_scale_f32_16x16x128_f8f6f4 v[20:23], v[136:143], v[210:217], v[20:23], v254, v254 op_sel_hi:[0,0,0]
	v_mfma_scale_f32_16x16x128_f8f6f4 v[16:19], v[128:135], v[210:217], v[16:19], v254, v254 op_sel_hi:[0,0,0]
	v_mfma_scale_f32_16x16x128_f8f6f4 v[4:7], v[136:143], v[218:225], v[4:7], v254, v254 op_sel_hi:[0,0,0]
	v_mfma_scale_f32_16x16x128_f8f6f4 v[0:3], v[128:135], v[218:225], v[0:3], v254, v254 op_sel_hi:[0,0,0]
	s_setprio 0
	s_barrier
	s_add_i32 s53, s53, 2
	s_add_u32 s28, s28, 0x100
	s_addc_u32 s29, s29, 0
	s_add_u32 s50, s50, 0x100
	s_addc_u32 s51, s51, 0
	s_cmp_gt_u32 s53, 13
	s_cbranch_scc0 .LBB0_208
	s_and_b64 vcc, exec, s[14:15]
	s_cbranch_vccz .LBB0_211
	s_barrier

; #define PG8_STAGE(bufoff, gbase, voff) do { _Pragma("unroll") for (int _i = 0; _i < 2; ++_i) \
;         __builtin_amdgcn_global_load_lds((const unsigned*)((const char*)(gbase) + (voff)[_i]), (LAS unsigned*)(lds + (bufoff) + ldsw + _i * 8192), 16, 0, 0); } while (0)
; #define PG8_LDA(dst, b, h) do { _Pragma("unroll") for (int m = 0; m < 4; ++m) _Pragma("unroll") for (int k = 0; k < 2; ++k) dst[m][k] = *(const LAS bf16x8*)(lds + PG8_SA(b, h) + aoff + m * 2048 + k * 1024); } while (0)
; #define PG8_LDB(dst, b, h) do { _Pragma("unroll") for (int n = 0; n < 2; ++n) _Pragma("unroll") for (int k = 0; k < 2; ++k) dst[n][k] = *(const LAS bf16x8*)(lds + PG8_SB(b, h) + boff + n * 2048 + k * 1024); } while (0)
; #define PG8_WAIT_V(n) asm volatile("s_waitcnt vmcnt(" #n ")" ::: "memory")
; #define PG8_WAIT_L(n) asm volatile("s_waitcnt lgkmcnt(" #n ")" ::: "memory")
; #define PG8_BAR __builtin_amdgcn_s_barrier()
; #define PG8_SCHED __builtin_amdgcn_sched_barrier(0)
; template <class Epi, class Sched, bool F8 = false>
; __device__ __forceinline__ void gemm_phase(LAS unsigned char* lds, const Gemm g, const Sched& S, const Epi& E) {
;     ...
;             const bool last = (t == nt - 2);
;             const char* a1 = cA + (size_t)(t + 1) * kstep;
;             const char* a2 = last ? nA : cA + (size_t)(t + 2) * kstep; const char* b2 = last ? nB : cB + (size_t)(t + 2) * kstep;
;             const char* a3 = a2 + kstep; const char* b3 = b2 + kstep;
;             PG8_LDB(B0, 0, 0); PG8_LDB(B1, 0, 1); PG8_SCHED; PG8_LDA(At, 0, 0); PG8_STAGE(PG8_SA(1, 1), a1 + hstepA, voffA);
;             PG8_WAIT_V(8); PG8_WAIT_L(0); PG8_BAR; PG8_MMA(0, 0, At, B0); PG8_MMA(0, 1, At, B1); PG8_BAR; PG8_SCHED;
;             PG8_LDA(At, 0, 1); PG8_STAGE(PG8_SB(0, 0), b2, voffB); PG8_STAGE(PG8_SB(0, 1), b2 + hstepB, voffB); PG8_STAGE(PG8_SA(0, 0), a2, voffA);
;             PG8_WAIT_V(8); PG8_WAIT_L(0); PG8_BAR; PG8_MMA(1, 0, At, B0); PG8_MMA(1, 1, At, B1); PG8_BAR; PG8_SCHED;
;             PG8_LDB(B0, 1, 0); PG8_LDB(B1, 1, 1); PG8_SCHED; PG8_LDA(At, 1, 0); PG8_STAGE(PG8_SA(0, 1), a2 + hstepA, voffA);
;             PG8_WAIT_V(8); PG8_WAIT_L(0); PG8_BAR; PG8_MMA(0, 0, At, B0); PG8_MMA(0, 1, At, B1); PG8_BAR; PG8_SCHED;
.LBB0_356:
	ds_read_b128 v[168:171], v158
	ds_read_b128 v[172:175], v158 offset:1024
	ds_read_b128 v[176:179], v158 offset:2048
	ds_read_b128 v[180:183], v158 offset:3072
	ds_read_b128 v[184:187], v160
	ds_read_b128 v[192:195], v160 offset:1024
	ds_read_b128 v[196:199], v160 offset:2048
	ds_read_b128 v[200:203], v160 offset:3072
	s_add_u32 s8, s30, 0x100
	s_addc_u32 s9, s31, 0
	s_cmp_eq_u32 s59, 4
	s_cselect_b32 s37, s25, s9
	s_cselect_b32 s36, s24, s8
	s_cselect_b32 s35, s10, s58
	s_cselect_b32 s34, s21, s29
	s_add_i32 m0, s40, 0xc000
	ds_read_b128 v[204:207], v159
	ds_read_b128 v[208:211], v159 offset:1024
	ds_read_b128 v[212:215], v159 offset:2048
	ds_read_b128 v[216:219], v159 offset:3072
	ds_read_b128 v[220:223], v159 offset:4096
	ds_read_b128 v[224:227], v159 offset:5120
	ds_read_b128 v[228:231], v159 offset:6144
	ds_read_b128 v[232:235], v159 offset:7168
	global_load_lds_dwordx4 v144, s[30:31]
	s_add_i32 m0, s40, 0xe000
	s_nop 0
	global_load_lds_dwordx4 v146, s[30:31]
	s_waitcnt vmcnt(8)
	s_waitcnt lgkmcnt(0)
	s_barrier
	s_setprio 1
	s_waitcnt lgkmcnt(0)
	v_mfma_f32_16x16x32_bf16 v[124:127], v[168:171], v[204:207], v[124:127]
	v_mfma_f32_16x16x32_bf16 v[120:123], v[176:179], v[204:207], v[120:123]
	v_mfma_f32_16x16x32_bf16 v[108:111], v[168:171], v[212:215], v[108:111]
	v_mfma_f32_16x16x32_bf16 v[104:107], v[176:179], v[212:215], v[104:107]
	v_mfma_f32_16x16x32_bf16 v[92:95], v[168:171], v[220:223], v[92:95]
	v_mfma_f32_16x16x32_bf16 v[88:91], v[176:179], v[220:223], v[88:91]
	v_mfma_f32_16x16x32_bf16 v[76:79], v[168:171], v[228:231], v[76:79]
	v_mfma_f32_16x16x32_bf16 v[72:75], v[176:179], v[228:231], v[72:75]
	v_mfma_f32_16x16x32_bf16 v[124:127], v[172:175], v[208:211], v[124:127]
	v_mfma_f32_16x16x32_bf16 v[120:123], v[180:183], v[208:211], v[120:123]
	v_mfma_f32_16x16x32_bf16 v[108:111], v[172:175], v[216:219], v[108:111]
	v_mfma_f32_16x16x32_bf16 v[104:107], v[180:183], v[216:219], v[104:107]
	v_mfma_f32_16x16x32_bf16 v[92:95], v[172:175], v[224:227], v[92:95]
	v_mfma_f32_16x16x32_bf16 v[88:91], v[180:183], v[224:227], v[88:91]
	v_mfma_f32_16x16x32_bf16 v[76:79], v[172:175], v[232:235], v[76:79]
	v_mfma_f32_16x16x32_bf16 v[72:75], v[180:183], v[232:235], v[72:75]
	v_mfma_f32_16x16x32_bf16 v[116:119], v[184:187], v[204:207], v[116:119]
	v_mfma_f32_16x16x32_bf16 v[112:115], v[196:199], v[204:207], v[112:115]
	v_mfma_f32_16x16x32_bf16 v[100:103], v[184:187], v[212:215], v[100:103]
	v_mfma_f32_16x16x32_bf16 v[96:99], v[196:199], v[212:215], v[96:99]
	v_mfma_f32_16x16x32_bf16 v[84:87], v[184:187], v[220:223], v[84:87]
	v_mfma_f32_16x16x32_bf16 v[80:83], v[196:199], v[220:223], v[80:83]
	v_mfma_f32_16x16x32_bf16 v[68:71], v[184:187], v[228:231], v[68:71]
	v_mfma_f32_16x16x32_bf16 v[64:67], v[196:199], v[228:231], v[64:67]
	v_mfma_f32_16x16x32_bf16 v[116:119], v[192:195], v[208:211], v[116:119]
	v_mfma_f32_16x16x32_bf16 v[112:115], v[200:203], v[208:211], v[112:115]
	v_mfma_f32_16x16x32_bf16 v[100:103], v[192:195], v[216:219], v[100:103]
	v_mfma_f32_16x16x32_bf16 v[96:99], v[200:203], v[216:219], v[96:99]
	v_mfma_f32_16x16x32_bf16 v[84:87], v[192:195], v[224:227], v[84:87]
	v_mfma_f32_16x16x32_bf16 v[80:83], v[200:203], v[224:227], v[80:83]
	v_mfma_f32_16x16x32_bf16 v[68:71], v[192:195], v[232:235], v[68:71]
	v_mfma_f32_16x16x32_bf16 v[64:67], v[200:203], v[232:235], v[64:67]
	s_setprio 0
	s_barrier
	s_add_i32 s30, s50, s39
	v_lshl_add_u64 v[152:153], s[34:35], 0, v[130:131]
	s_mov_b32 m0, s30
	ds_read_b128 v[204:207], v159 offset:16384
	ds_read_b128 v[208:211], v159 offset:17408
	ds_read_b128 v[212:215], v159 offset:18432
	ds_read_b128 v[216:219], v159 offset:19456
	ds_read_b128 v[220:223], v159 offset:20480
	ds_read_b128 v[224:227], v159 offset:21504
	ds_read_b128 v[228:231], v159 offset:22528
	ds_read_b128 v[232:235], v159 offset:23552
	global_load_lds_dwordx4 v[152:153], off
	s_add_i32 m0, s30, 0x2000
	s_add_u32 s30, s34, 0x20000
	v_lshl_add_u64 v[188:189], s[34:35], 0, v[134:135]
	s_addc_u32 s31, s35, 0
	s_add_i32 s72, s51, s39
	global_load_lds_dwordx4 v[188:189], off
	s_mov_b32 m0, s72
	v_lshl_add_u64 v[238:239], s[36:37], 0, v[132:133]
	global_load_lds_dwordx4 v130, s[30:31]
	s_add_i32 m0, s72, 0x2000
	s_nop 0
	global_load_lds_dwordx4 v134, s[30:31]
	v_lshl_add_u64 v[236:237], s[36:37], 0, v[128:129]
	s_mov_b32 m0, s40
	s_nop 0
	global_load_lds_dwordx4 v[236:237], off
	s_mov_b32 m0, s41
	s_nop 0
	global_load_lds_dwordx4 v[238:239], off
	s_waitcnt vmcnt(8)
	s_waitcnt lgkmcnt(0)
	s_barrier
	s_setprio 1
	s_waitcnt lgkmcnt(0)
	v_mfma_f32_16x16x32_bf16 v[60:63], v[168:171], v[204:207], v[60:63]
	v_mfma_f32_16x16x32_bf16 v[56:59], v[176:179], v[204:207], v[56:59]
	v_mfma_f32_16x16x32_bf16 v[44:47], v[168:171], v[212:215], v[44:47]
	v_mfma_f32_16x16x32_bf16 v[40:43], v[176:179], v[212:215], v[40:43]
	v_mfma_f32_16x16x32_bf16 v[28:31], v[168:171], v[220:223], v[28:31]
	v_mfma_f32_16x16x32_bf16 v[24:27], v[176:179], v[220:223], v[24:27]
	v_mfma_f32_16x16x32_bf16 v[12:15], v[168:171], v[228:231], v[12:15]
	v_mfma_f32_16x16x32_bf16 v[8:11], v[176:179], v[228:231], v[8:11]
	v_mfma_f32_16x16x32_bf16 v[60:63], v[172:175], v[208:211], v[60:63]
	v_mfma_f32_16x16x32_bf16 v[56:59], v[180:183], v[208:211], v[56:59]
	v_mfma_f32_16x16x32_bf16 v[44:47], v[172:175], v[216:219], v[44:47]
	v_mfma_f32_16x16x32_bf16 v[40:43], v[180:183], v[216:219], v[40:43]
	v_mfma_f32_16x16x32_bf16 v[28:31], v[172:175], v[224:227], v[28:31]
	v_mfma_f32_16x16x32_bf16 v[24:27], v[180:183], v[224:227], v[24:27]
	v_mfma_f32_16x16x32_bf16 v[12:15], v[172:175], v[232:235], v[12:15]
	v_mfma_f32_16x16x32_bf16 v[8:11], v[180:183], v[232:235], v[8:11]
	v_mfma_f32_16x16x32_bf16 v[52:55], v[184:187], v[204:207], v[52:55]
	v_mfma_f32_16x16x32_bf16 v[48:51], v[196:199], v[204:207], v[48:51]
	v_mfma_f32_16x16x32_bf16 v[36:39], v[184:187], v[212:215], v[36:39]
	v_mfma_f32_16x16x32_bf16 v[32:35], v[196:199], v[212:215], v[32:35]
	v_mfma_f32_16x16x32_bf16 v[20:23], v[184:187], v[220:223], v[20:23]
	v_mfma_f32_16x16x32_bf16 v[16:19], v[196:199], v[220:223], v[16:19]
	v_mfma_f32_16x16x32_bf16 v[4:7], v[184:187], v[228:231], v[4:7]
	v_mfma_f32_16x16x32_bf16 v[0:3], v[196:199], v[228:231], v[0:3]
	v_mfma_f32_16x16x32_bf16 v[52:55], v[192:195], v[208:211], v[52:55]
	v_mfma_f32_16x16x32_bf16 v[48:51], v[200:203], v[208:211], v[48:51]
	v_mfma_f32_16x16x32_bf16 v[36:39], v[192:195], v[216:219], v[36:39]
	v_mfma_f32_16x16x32_bf16 v[32:35], v[200:203], v[216:219], v[32:35]
	v_mfma_f32_16x16x32_bf16 v[20:23], v[192:195], v[224:227], v[20:23]
	v_mfma_f32_16x16x32_bf16 v[16:19], v[200:203], v[224:227], v[16:19]
	v_mfma_f32_16x16x32_bf16 v[4:7], v[192:195], v[232:235], v[4:7]
	v_mfma_f32_16x16x32_bf16 v[0:3], v[200:203], v[232:235], v[0:3]
	s_setprio 0
	s_barrier
; #define PG8_STAGE(bufoff, gbase, voff) do { _Pragma("unroll") for (int _i = 0; _i < 2; ++_i) \
;         __builtin_amdgcn_global_load_lds((const unsigned*)((const char*)(gbase) + (voff)[_i]), (LAS unsigned*)(lds + (bufoff) + ldsw + _i * 8192), 16, 0, 0); } while (0)
; #define PG8_LDA(dst, b, h) do { _Pragma("unroll") for (int m = 0; m < 4; ++m) _Pragma("unroll") for (int k = 0; k < 2; ++k) dst[m][k] = *(const LAS bf16x8*)(lds + PG8_SA(b, h) + aoff + m * 2048 + k * 1024); } while (0)
; #define PG8_WAIT_V(n) asm volatile("s_waitcnt vmcnt(" #n ")" ::: "memory")
; #define PG8_WAIT_L(n) asm volatile("s_waitcnt lgkmcnt(" #n ")" ::: "memory")
; #define PG8_BAR __builtin_amdgcn_s_barrier()
; #define PG8_SCHED __builtin_amdgcn_sched_barrier(0)
; template <class Epi, class Sched, bool F8 = false>
; __device__ __forceinline__ void gemm_phase(LAS unsigned char* lds, const Gemm g, const Sched& S, const Epi& E) {
;     ...
;             PG8_WAIT_V(8); PG8_WAIT_L(0); PG8_BAR; PG8_MMA(0, 0, At, B0); PG8_MMA(0, 1, At, B1); PG8_BAR; PG8_SCHED;
;             PG8_LDA(At, 1, 1); PG8_STAGE(PG8_SB(1, 0), b3, voffB); PG8_STAGE(PG8_SB(1, 1), b3 + hstepB, voffB); PG8_STAGE(PG8_SA(1, 0), a3, voffA);
;             PG8_WAIT_V(8); PG8_WAIT_L(0); PG8_BAR; PG8_MMA(1, 0, At, B0); PG8_MMA(1, 1, At, B1); PG8_BAR; PG8_SCHED;
;         }
;         if (wr == 0) PG8_BAR;
	s_add_i32 s72, 0, 0x18000
	v_add_u32_e32 v154, s72, v156
	s_add_i32 s73, 0, 0x1c000
	ds_read_b128 v[168:171], v154
	ds_read_b128 v[172:175], v154 offset:1024
	ds_read_b128 v[176:179], v154 offset:2048
	ds_read_b128 v[180:183], v154 offset:3072
	v_add_u32_e32 v154, s73, v156
	ds_read_b128 v[184:187], v154
	ds_read_b128 v[192:195], v154 offset:1024
	ds_read_b128 v[196:199], v154 offset:2048
	ds_read_b128 v[200:203], v154 offset:3072
	s_add_u32 s30, s36, 0xc0000
	s_addc_u32 s31, s37, 0
	s_mov_b32 m0, s42
	ds_read_b128 v[204:207], v159 offset:32768
	ds_read_b128 v[208:211], v159 offset:33792
	ds_read_b128 v[212:215], v159 offset:34816
	ds_read_b128 v[216:219], v159 offset:35840
	ds_read_b128 v[220:223], v159 offset:36864
	ds_read_b128 v[224:227], v159 offset:37888
	ds_read_b128 v[228:231], v159 offset:38912
	ds_read_b128 v[232:235], v159 offset:39936
	global_load_lds_dwordx4 v128, s[30:31]
	s_mov_b32 m0, s43
	s_nop 0
	global_load_lds_dwordx4 v132, s[30:31]
	s_waitcnt vmcnt(8)
	s_waitcnt lgkmcnt(0)
	s_barrier
	s_setprio 1
	s_waitcnt lgkmcnt(0)
	v_mfma_f32_16x16x32_bf16 v[124:127], v[168:171], v[204:207], v[124:127]
	v_mfma_f32_16x16x32_bf16 v[120:123], v[176:179], v[204:207], v[120:123]
	v_mfma_f32_16x16x32_bf16 v[108:111], v[168:171], v[212:215], v[108:111]
	v_mfma_f32_16x16x32_bf16 v[104:107], v[176:179], v[212:215], v[104:107]
	v_mfma_f32_16x16x32_bf16 v[92:95], v[168:171], v[220:223], v[92:95]
	v_mfma_f32_16x16x32_bf16 v[88:91], v[176:179], v[220:223], v[88:91]
	v_mfma_f32_16x16x32_bf16 v[76:79], v[168:171], v[228:231], v[76:79]
	v_mfma_f32_16x16x32_bf16 v[72:75], v[176:179], v[228:231], v[72:75]
	v_mfma_f32_16x16x32_bf16 v[124:127], v[172:175], v[208:211], v[124:127]
	v_mfma_f32_16x16x32_bf16 v[120:123], v[180:183], v[208:211], v[120:123]
	v_mfma_f32_16x16x32_bf16 v[108:111], v[172:175], v[216:219], v[108:111]
	v_mfma_f32_16x16x32_bf16 v[104:107], v[180:183], v[216:219], v[104:107]
	v_mfma_f32_16x16x32_bf16 v[92:95], v[172:175], v[224:227], v[92:95]
	v_mfma_f32_16x16x32_bf16 v[88:91], v[180:183], v[224:227], v[88:91]
	v_mfma_f32_16x16x32_bf16 v[76:79], v[172:175], v[232:235], v[76:79]
	v_mfma_f32_16x16x32_bf16 v[72:75], v[180:183], v[232:235], v[72:75]
	v_mfma_f32_16x16x32_bf16 v[116:119], v[184:187], v[204:207], v[116:119]
	v_mfma_f32_16x16x32_bf16 v[112:115], v[196:199], v[204:207], v[112:115]
	v_mfma_f32_16x16x32_bf16 v[100:103], v[184:187], v[212:215], v[100:103]
	v_mfma_f32_16x16x32_bf16 v[96:99], v[196:199], v[212:215], v[96:99]
	v_mfma_f32_16x16x32_bf16 v[84:87], v[184:187], v[220:223], v[84:87]
	v_mfma_f32_16x16x32_bf16 v[80:83], v[196:199], v[220:223], v[80:83]
	v_mfma_f32_16x16x32_bf16 v[68:71], v[184:187], v[228:231], v[68:71]
	v_mfma_f32_16x16x32_bf16 v[64:67], v[196:199], v[228:231], v[64:67]
	v_mfma_f32_16x16x32_bf16 v[116:119], v[192:195], v[208:211], v[116:119]
	v_mfma_f32_16x16x32_bf16 v[112:115], v[200:203], v[208:211], v[112:115]
	v_mfma_f32_16x16x32_bf16 v[100:103], v[192:195], v[216:219], v[100:103]
	v_mfma_f32_16x16x32_bf16 v[96:99], v[200:203], v[216:219], v[96:99]
	v_mfma_f32_16x16x32_bf16 v[84:87], v[192:195], v[224:227], v[84:87]
	v_mfma_f32_16x16x32_bf16 v[80:83], v[200:203], v[224:227], v[80:83]
	v_mfma_f32_16x16x32_bf16 v[68:71], v[192:195], v[232:235], v[68:71]
	v_mfma_f32_16x16x32_bf16 v[64:67], v[200:203], v[232:235], v[64:67]
	s_setprio 0
	s_barrier
	s_add_i32 s30, s72, s39
	s_add_i32 m0, s30, 0xffffff80
	ds_read_b128 v[204:207], v159 offset:49152
	ds_read_b128 v[208:211], v159 offset:50176
	ds_read_b128 v[212:215], v159 offset:51200
	ds_read_b128 v[216:219], v159 offset:52224
	ds_read_b128 v[220:223], v159 offset:53248
	ds_read_b128 v[224:227], v159 offset:54272
	ds_read_b128 v[228:231], v159 offset:55296
	ds_read_b128 v[232:235], v159 offset:56320
	global_load_lds_dwordx4 v[152:153], off offset:128
	s_add_i32 m0, s30, 0x1f80
	s_add_u32 s30, s34, 0x20080
	s_addc_u32 s31, s35, 0
	s_add_i32 s34, s73, s39
	global_load_lds_dwordx4 v[188:189], off offset:128
	s_mov_b32 m0, s34
	s_nop 0
	global_load_lds_dwordx4 v130, s[30:31]
	s_add_i32 m0, s34, 0x2000
	s_nop 0
	global_load_lds_dwordx4 v134, s[30:31]
	s_add_i32 m0, s45, 0xffffff80
	s_nop 0
	global_load_lds_dwordx4 v[236:237], off offset:128
	s_add_i32 m0, s47, 0xffffff80
	s_nop 0
	global_load_lds_dwordx4 v[238:239], off offset:128
	s_waitcnt vmcnt(8)
	s_waitcnt lgkmcnt(0)
	s_barrier
	s_setprio 1
	s_waitcnt lgkmcnt(0)
	v_mfma_f32_16x16x32_bf16 v[60:63], v[168:171], v[204:207], v[60:63]
	v_mfma_f32_16x16x32_bf16 v[56:59], v[176:179], v[204:207], v[56:59]
	v_mfma_f32_16x16x32_bf16 v[44:47], v[168:171], v[212:215], v[44:47]
	v_mfma_f32_16x16x32_bf16 v[40:43], v[176:179], v[212:215], v[40:43]
	v_mfma_f32_16x16x32_bf16 v[28:31], v[168:171], v[220:223], v[28:31]
	v_mfma_f32_16x16x32_bf16 v[24:27], v[176:179], v[220:223], v[24:27]
	v_mfma_f32_16x16x32_bf16 v[12:15], v[168:171], v[228:231], v[12:15]
	v_mfma_f32_16x16x32_bf16 v[8:11], v[176:179], v[228:231], v[8:11]
	v_mfma_f32_16x16x32_bf16 v[60:63], v[172:175], v[208:211], v[60:63]
	v_mfma_f32_16x16x32_bf16 v[56:59], v[180:183], v[208:211], v[56:59]
	v_mfma_f32_16x16x32_bf16 v[44:47], v[172:175], v[216:219], v[44:47]
	v_mfma_f32_16x16x32_bf16 v[40:43], v[180:183], v[216:219], v[40:43]
	v_mfma_f32_16x16x32_bf16 v[28:31], v[172:175], v[224:227], v[28:31]
	v_mfma_f32_16x16x32_bf16 v[24:27], v[180:183], v[224:227], v[24:27]
	v_mfma_f32_16x16x32_bf16 v[12:15], v[172:175], v[232:235], v[12:15]
	v_mfma_f32_16x16x32_bf16 v[8:11], v[180:183], v[232:235], v[8:11]
	v_mfma_f32_16x16x32_bf16 v[52:55], v[184:187], v[204:207], v[52:55]
	v_mfma_f32_16x16x32_bf16 v[48:51], v[196:199], v[204:207], v[48:51]
	v_mfma_f32_16x16x32_bf16 v[36:39], v[184:187], v[212:215], v[36:39]
	v_mfma_f32_16x16x32_bf16 v[32:35], v[196:199], v[212:215], v[32:35]
	v_mfma_f32_16x16x32_bf16 v[20:23], v[184:187], v[220:223], v[20:23]
	v_mfma_f32_16x16x32_bf16 v[16:19], v[196:199], v[220:223], v[16:19]
	v_mfma_f32_16x16x32_bf16 v[4:7], v[184:187], v[228:231], v[4:7]
	v_mfma_f32_16x16x32_bf16 v[0:3], v[196:199], v[228:231], v[0:3]
	v_mfma_f32_16x16x32_bf16 v[52:55], v[192:195], v[208:211], v[52:55]
	v_mfma_f32_16x16x32_bf16 v[48:51], v[200:203], v[208:211], v[48:51]
	v_mfma_f32_16x16x32_bf16 v[36:39], v[192:195], v[216:219], v[36:39]
	v_mfma_f32_16x16x32_bf16 v[32:35], v[200:203], v[216:219], v[32:35]
	v_mfma_f32_16x16x32_bf16 v[20:23], v[192:195], v[224:227], v[20:23]
	v_mfma_f32_16x16x32_bf16 v[16:19], v[200:203], v[224:227], v[16:19]
	v_mfma_f32_16x16x32_bf16 v[4:7], v[192:195], v[232:235], v[4:7]
	v_mfma_f32_16x16x32_bf16 v[0:3], v[200:203], v[232:235], v[0:3]
	s_setprio 0
	s_barrier
	s_add_i32 s59, s59, 2
	s_add_u32 s29, s29, 0x100
	s_addc_u32 s58, s58, 0
	s_cmp_gt_u32 s59, 5
	s_mov_b64 s[30:31], s[8:9]
	s_cbranch_scc0 .LBB0_356
	s_and_b64 vcc, exec, s[18:19]
	s_cbranch_vccz .LBB0_359
	s_barrier

; #define PG8_STAGE(bufoff, gbase, voff) do { _Pragma("unroll") for (int _i = 0; _i < 2; ++_i) \
;         __builtin_amdgcn_global_load_lds((const unsigned*)((const char*)(gbase) + (voff)[_i]), (LAS unsigned*)(lds + (bufoff) + ldsw + _i * 8192), 16, 0, 0); } while (0)
; #define PG8_LDA(dst, b, h) do { _Pragma("unroll") for (int m = 0; m < 4; ++m) _Pragma("unroll") for (int k = 0; k < 2; ++k) dst[m][k] = *(const LAS bf16x8*)(lds + PG8_SA(b, h) + aoff + m * 2048 + k * 1024); } while (0)
; #define PG8_LDB(dst, b, h) do { _Pragma("unroll") for (int n = 0; n < 2; ++n) _Pragma("unroll") for (int k = 0; k < 2; ++k) dst[n][k] = *(const LAS bf16x8*)(lds + PG8_SB(b, h) + boff + n * 2048 + k * 1024); } while (0)
; #define PG8_WAIT_V(n) asm volatile("s_waitcnt vmcnt(" #n ")" ::: "memory")
; #define PG8_WAIT_L(n) asm volatile("s_waitcnt lgkmcnt(" #n ")" ::: "memory")
; #define PG8_BAR __builtin_amdgcn_s_barrier()
; #define PG8_SCHED __builtin_amdgcn_sched_barrier(0)
; template <class Epi, class Sched, bool F8 = false>
; __device__ __forceinline__ void gemm_phase(LAS unsigned char* lds, const Gemm g, const Sched& S, const Epi& E) {
;     ...
;             const bool last = (t == nt - 2);
;             const char* a1 = cA + (size_t)(t + 1) * kstep;
;             const char* a2 = last ? nA : cA + (size_t)(t + 2) * kstep; const char* b2 = last ? nB : cB + (size_t)(t + 2) * kstep;
;             const char* a3 = a2 + kstep; const char* b3 = b2 + kstep;
;             PG8_LDB(B0, 0, 0); PG8_LDB(B1, 0, 1); PG8_SCHED; PG8_LDA(At, 0, 0); PG8_STAGE(PG8_SA(1, 1), a1 + hstepA, voffA);
;             PG8_WAIT_V(8); PG8_WAIT_L(0); PG8_BAR; PG8_MMA(0, 0, At, B0); PG8_MMA(0, 1, At, B1); PG8_BAR; PG8_SCHED;
;             PG8_LDA(At, 0, 1); PG8_STAGE(PG8_SB(0, 0), b2, voffB); PG8_STAGE(PG8_SB(0, 1), b2 + hstepB, voffB); PG8_STAGE(PG8_SA(0, 0), a2, voffA);
;             PG8_WAIT_V(8); PG8_WAIT_L(0); PG8_BAR; PG8_MMA(1, 0, At, B0); PG8_MMA(1, 1, At, B1); PG8_BAR; PG8_SCHED;
;             PG8_LDB(B0, 1, 0); PG8_LDB(B1, 1, 1); PG8_SCHED; PG8_LDA(At, 1, 0); PG8_STAGE(PG8_SA(0, 1), a2 + hstepA, voffA);
;             PG8_WAIT_V(8); PG8_WAIT_L(0); PG8_BAR; PG8_MMA(0, 0, At, B0); PG8_MMA(0, 1, At, B1); PG8_BAR; PG8_SCHED;
.LBB0_753:
	v_add_u32_e32 v140, s48, v197
	v_add_u32_e32 v156, s91, v197
	ds_read_b128 v[128:131], v140
	ds_read_b128 v[132:135], v140 offset:1024
	ds_read_b128 v[136:139], v140 offset:2048
	ds_read_b128 v[140:143], v140 offset:3072
	ds_read_b128 v[144:147], v156
	ds_read_b128 v[148:151], v156 offset:1024
	ds_read_b128 v[152:155], v156 offset:2048
	ds_read_b128 v[156:159], v156 offset:3072
	s_add_i32 s80, s34, 2
	s_add_u32 s35, s30, 0xfff80080
	s_addc_u32 s36, s31, -1
	s_cmp_eq_u32 s77, s34
	s_cselect_b32 s34, s76, s78
	s_cselect_b32 s37, s25, s36
	s_cselect_b32 s36, s75, s35
	s_cselect_b32 s35, s21, s79
	s_add_i32 m0, s40, 0xc000
	ds_read_b128 v[160:163], v199
	ds_read_b128 v[164:167], v199 offset:1024
	ds_read_b128 v[168:171], v199 offset:2048
	ds_read_b128 v[172:175], v199 offset:3072
	ds_read_b128 v[200:203], v199 offset:4096
	ds_read_b128 v[204:207], v199 offset:5120
	ds_read_b128 v[208:211], v199 offset:6144
	ds_read_b128 v[212:215], v199 offset:7168
	global_load_lds_dwordx4 v186, s[30:31]
	s_add_i32 m0, s40, 0xe000
	s_nop 0
	global_load_lds_dwordx4 v188, s[30:31]
	s_waitcnt vmcnt(8)
	s_waitcnt lgkmcnt(0)
	s_barrier
	s_setprio 1
	s_waitcnt lgkmcnt(0)
	v_mfma_f32_16x16x32_bf16 v[124:127], v[128:131], v[160:163], v[124:127]
	v_mfma_f32_16x16x32_bf16 v[120:123], v[136:139], v[160:163], v[120:123]
	v_mfma_f32_16x16x32_bf16 v[116:119], v[128:131], v[168:171], v[116:119]
	v_mfma_f32_16x16x32_bf16 v[112:115], v[136:139], v[168:171], v[112:115]
	v_mfma_f32_16x16x32_bf16 v[108:111], v[128:131], v[200:203], v[108:111]
	v_mfma_f32_16x16x32_bf16 v[104:107], v[136:139], v[200:203], v[104:107]
	v_mfma_f32_16x16x32_bf16 v[100:103], v[128:131], v[208:211], v[100:103]
	v_mfma_f32_16x16x32_bf16 v[96:99], v[136:139], v[208:211], v[96:99]
	v_mfma_f32_16x16x32_bf16 v[124:127], v[132:135], v[164:167], v[124:127]
	v_mfma_f32_16x16x32_bf16 v[120:123], v[140:143], v[164:167], v[120:123]
	v_mfma_f32_16x16x32_bf16 v[116:119], v[132:135], v[172:175], v[116:119]
	v_mfma_f32_16x16x32_bf16 v[112:115], v[140:143], v[172:175], v[112:115]
	v_mfma_f32_16x16x32_bf16 v[108:111], v[132:135], v[204:207], v[108:111]
	v_mfma_f32_16x16x32_bf16 v[104:107], v[140:143], v[204:207], v[104:107]
	v_mfma_f32_16x16x32_bf16 v[100:103], v[132:135], v[212:215], v[100:103]
	v_mfma_f32_16x16x32_bf16 v[96:99], v[140:143], v[212:215], v[96:99]
	v_mfma_f32_16x16x32_bf16 v[92:95], v[144:147], v[160:163], v[92:95]
	v_mfma_f32_16x16x32_bf16 v[88:91], v[152:155], v[160:163], v[88:91]
	v_mfma_f32_16x16x32_bf16 v[84:87], v[144:147], v[168:171], v[84:87]
	v_mfma_f32_16x16x32_bf16 v[80:83], v[152:155], v[168:171], v[80:83]
	v_mfma_f32_16x16x32_bf16 v[76:79], v[144:147], v[200:203], v[76:79]
	v_mfma_f32_16x16x32_bf16 v[72:75], v[152:155], v[200:203], v[72:75]
	v_mfma_f32_16x16x32_bf16 v[68:71], v[144:147], v[208:211], v[68:71]
	v_mfma_f32_16x16x32_bf16 v[64:67], v[152:155], v[208:211], v[64:67]
	v_mfma_f32_16x16x32_bf16 v[92:95], v[148:151], v[164:167], v[92:95]
	v_mfma_f32_16x16x32_bf16 v[88:91], v[156:159], v[164:167], v[88:91]
	v_mfma_f32_16x16x32_bf16 v[84:87], v[148:151], v[172:175], v[84:87]
	v_mfma_f32_16x16x32_bf16 v[80:83], v[156:159], v[172:175], v[80:83]
	v_mfma_f32_16x16x32_bf16 v[76:79], v[148:151], v[204:207], v[76:79]
	v_mfma_f32_16x16x32_bf16 v[72:75], v[156:159], v[204:207], v[72:75]
	v_mfma_f32_16x16x32_bf16 v[68:71], v[148:151], v[212:215], v[68:71]
	v_mfma_f32_16x16x32_bf16 v[64:67], v[156:159], v[212:215], v[64:67]
	s_setprio 0
	s_barrier
	s_add_i32 s81, s48, s38
	v_lshl_add_u64 v[216:217], s[34:35], 0, v[180:181]
	s_mov_b32 m0, s81
	ds_read_b128 v[160:163], v199 offset:16384
	ds_read_b128 v[164:167], v199 offset:17408
	ds_read_b128 v[168:171], v199 offset:18432
	ds_read_b128 v[172:175], v199 offset:19456
	ds_read_b128 v[200:203], v199 offset:20480
	ds_read_b128 v[204:207], v199 offset:21504
	ds_read_b128 v[208:211], v199 offset:22528
	ds_read_b128 v[212:215], v199 offset:23552
	global_load_lds_dwordx4 v[216:217], off
	s_add_i32 m0, s81, 0x2000
	s_add_u32 s82, s34, 0x80000
	v_lshl_add_u64 v[218:219], s[34:35], 0, v[176:177]
	s_addc_u32 s83, s35, 0
	s_add_i32 s81, s91, s38
	global_load_lds_dwordx4 v[218:219], off
	s_mov_b32 m0, s81
	v_lshl_add_u64 v[222:223], s[36:37], 0, v[178:179]
	global_load_lds_dwordx4 v180, s[82:83]
	s_add_i32 m0, s81, 0x2000
	s_nop 0
	global_load_lds_dwordx4 v176, s[82:83]
	v_lshl_add_u64 v[220:221], s[36:37], 0, v[182:183]
	s_mov_b32 m0, s40
	s_nop 0
	global_load_lds_dwordx4 v[220:221], off
	s_mov_b32 m0, s41
	s_nop 0
	global_load_lds_dwordx4 v[222:223], off
	s_waitcnt vmcnt(8)
	s_waitcnt lgkmcnt(0)
	s_barrier
; #define PG8_STAGE(bufoff, gbase, voff) do { _Pragma("unroll") for (int _i = 0; _i < 2; ++_i) \
;         __builtin_amdgcn_global_load_lds((const unsigned*)((const char*)(gbase) + (voff)[_i]), (LAS unsigned*)(lds + (bufoff) + ldsw + _i * 8192), 16, 0, 0); } while (0)
; #define PG8_LDA(dst, b, h) do { _Pragma("unroll") for (int m = 0; m < 4; ++m) _Pragma("unroll") for (int k = 0; k < 2; ++k) dst[m][k] = *(const LAS bf16x8*)(lds + PG8_SA(b, h) + aoff + m * 2048 + k * 1024); } while (0)
; #define PG8_LDB(dst, b, h) do { _Pragma("unroll") for (int n = 0; n < 2; ++n) _Pragma("unroll") for (int k = 0; k < 2; ++k) dst[n][k] = *(const LAS bf16x8*)(lds + PG8_SB(b, h) + boff + n * 2048 + k * 1024); } while (0)
; #define PG8_WAIT_V(n) asm volatile("s_waitcnt vmcnt(" #n ")" ::: "memory")
; #define PG8_WAIT_L(n) asm volatile("s_waitcnt lgkmcnt(" #n ")" ::: "memory")
; #define PG8_BAR __builtin_amdgcn_s_barrier()
; #define PG8_SCHED __builtin_amdgcn_sched_barrier(0)
; template <class Epi, class Sched, bool F8 = false>
; __device__ __forceinline__ void gemm_phase(LAS unsigned char* lds, const Gemm g, const Sched& S, const Epi& E) {
;     ...
;             PG8_LDB(B0, 0, 0); PG8_LDB(B1, 0, 1); PG8_SCHED; PG8_LDA(At, 0, 0); PG8_STAGE(PG8_SA(1, 1), a1 + hstepA, voffA);
;             PG8_WAIT_V(8); PG8_WAIT_L(0); PG8_BAR; PG8_MMA(0, 0, At, B0); PG8_MMA(0, 1, At, B1); PG8_BAR; PG8_SCHED;
;             PG8_LDA(At, 0, 1); PG8_STAGE(PG8_SB(0, 0), b2, voffB); PG8_STAGE(PG8_SB(0, 1), b2 + hstepB, voffB); PG8_STAGE(PG8_SA(0, 0), a2, voffA);
;             PG8_WAIT_V(8); PG8_WAIT_L(0); PG8_BAR; PG8_MMA(1, 0, At, B0); PG8_MMA(1, 1, At, B1); PG8_BAR; PG8_SCHED;
;             PG8_LDB(B0, 1, 0); PG8_LDB(B1, 1, 1); PG8_SCHED; PG8_LDA(At, 1, 0); PG8_STAGE(PG8_SA(0, 1), a2 + hstepA, voffA);
;             PG8_WAIT_V(8); PG8_WAIT_L(0); PG8_BAR; PG8_MMA(0, 0, At, B0); PG8_MMA(0, 1, At, B1); PG8_BAR; PG8_SCHED;
;             PG8_LDA(At, 1, 1); PG8_STAGE(PG8_SB(1, 0), b3, voffB); PG8_STAGE(PG8_SB(1, 1), b3 + hstepB, voffB); PG8_STAGE(PG8_SA(1, 0), a3, voffA);
;             PG8_WAIT_V(8); PG8_WAIT_L(0); PG8_BAR; PG8_MMA(1, 0, At, B0); PG8_MMA(1, 1, At, B1); PG8_BAR; PG8_SCHED;
	s_setprio 1
	s_waitcnt lgkmcnt(0)
	v_mfma_f32_16x16x32_bf16 v[60:63], v[128:131], v[160:163], v[60:63]
	v_mfma_f32_16x16x32_bf16 v[56:59], v[136:139], v[160:163], v[56:59]
	v_mfma_f32_16x16x32_bf16 v[52:55], v[128:131], v[168:171], v[52:55]
	v_mfma_f32_16x16x32_bf16 v[48:51], v[136:139], v[168:171], v[48:51]
	v_mfma_f32_16x16x32_bf16 v[44:47], v[128:131], v[200:203], v[44:47]
	v_mfma_f32_16x16x32_bf16 v[40:43], v[136:139], v[200:203], v[40:43]
	v_mfma_f32_16x16x32_bf16 v[36:39], v[128:131], v[208:211], v[36:39]
	v_mfma_f32_16x16x32_bf16 v[32:35], v[136:139], v[208:211], v[32:35]
	v_mfma_f32_16x16x32_bf16 v[60:63], v[132:135], v[164:167], v[60:63]
	v_mfma_f32_16x16x32_bf16 v[56:59], v[140:143], v[164:167], v[56:59]
	v_mfma_f32_16x16x32_bf16 v[52:55], v[132:135], v[172:175], v[52:55]
	v_mfma_f32_16x16x32_bf16 v[48:51], v[140:143], v[172:175], v[48:51]
	v_mfma_f32_16x16x32_bf16 v[44:47], v[132:135], v[204:207], v[44:47]
	v_mfma_f32_16x16x32_bf16 v[40:43], v[140:143], v[204:207], v[40:43]
	v_mfma_f32_16x16x32_bf16 v[36:39], v[132:135], v[212:215], v[36:39]
	v_mfma_f32_16x16x32_bf16 v[32:35], v[140:143], v[212:215], v[32:35]
	v_mfma_f32_16x16x32_bf16 v[28:31], v[144:147], v[160:163], v[28:31]
	v_mfma_f32_16x16x32_bf16 v[24:27], v[152:155], v[160:163], v[24:27]
	v_mfma_f32_16x16x32_bf16 v[20:23], v[144:147], v[168:171], v[20:23]
	v_mfma_f32_16x16x32_bf16 v[16:19], v[152:155], v[168:171], v[16:19]
	v_mfma_f32_16x16x32_bf16 v[12:15], v[144:147], v[200:203], v[12:15]
	v_mfma_f32_16x16x32_bf16 v[8:11], v[152:155], v[200:203], v[8:11]
	v_mfma_f32_16x16x32_bf16 v[4:7], v[144:147], v[208:211], v[4:7]
	v_mfma_f32_16x16x32_bf16 v[0:3], v[152:155], v[208:211], v[0:3]
	v_mfma_f32_16x16x32_bf16 v[28:31], v[148:151], v[164:167], v[28:31]
	v_mfma_f32_16x16x32_bf16 v[24:27], v[156:159], v[164:167], v[24:27]
	v_mfma_f32_16x16x32_bf16 v[20:23], v[148:151], v[172:175], v[20:23]
	v_mfma_f32_16x16x32_bf16 v[16:19], v[156:159], v[172:175], v[16:19]
	v_mfma_f32_16x16x32_bf16 v[12:15], v[148:151], v[204:207], v[12:15]
	v_mfma_f32_16x16x32_bf16 v[8:11], v[156:159], v[204:207], v[8:11]
	v_mfma_f32_16x16x32_bf16 v[4:7], v[148:151], v[212:215], v[4:7]
	v_mfma_f32_16x16x32_bf16 v[0:3], v[156:159], v[212:215], v[0:3]
	s_setprio 0
	s_barrier
	s_add_i32 s81, 0, 0x18000
	s_add_i32 s82, 0, 0x1c000
	v_add_u32_e32 v140, s81, v197
	v_add_u32_e32 v156, s82, v197
	ds_read_b128 v[128:131], v140
	ds_read_b128 v[132:135], v140 offset:1024
	ds_read_b128 v[136:139], v140 offset:2048
	ds_read_b128 v[140:143], v140 offset:3072
	ds_read_b128 v[144:147], v156
	ds_read_b128 v[148:151], v156 offset:1024
	ds_read_b128 v[152:155], v156 offset:2048
	ds_read_b128 v[156:159], v156 offset:3072
	s_add_u32 s36, s36, 0x80000
	s_addc_u32 s37, s37, 0
	s_mov_b32 m0, s42
	ds_read_b128 v[160:163], v199 offset:32768
	ds_read_b128 v[164:167], v199 offset:33792
	ds_read_b128 v[168:171], v199 offset:34816
	ds_read_b128 v[172:175], v199 offset:35840
	ds_read_b128 v[200:203], v199 offset:36864
	ds_read_b128 v[204:207], v199 offset:37888
	ds_read_b128 v[208:211], v199 offset:38912
	ds_read_b128 v[212:215], v199 offset:39936
	global_load_lds_dwordx4 v182, s[36:37]
	s_mov_b32 m0, s43
	s_nop 0
	global_load_lds_dwordx4 v178, s[36:37]
	s_waitcnt vmcnt(8)
	s_waitcnt lgkmcnt(0)
	s_barrier
	s_setprio 1
	s_waitcnt lgkmcnt(0)
	v_mfma_f32_16x16x32_bf16 v[124:127], v[128:131], v[160:163], v[124:127]
	v_mfma_f32_16x16x32_bf16 v[120:123], v[136:139], v[160:163], v[120:123]
	v_mfma_f32_16x16x32_bf16 v[116:119], v[128:131], v[168:171], v[116:119]
	v_mfma_f32_16x16x32_bf16 v[112:115], v[136:139], v[168:171], v[112:115]
	v_mfma_f32_16x16x32_bf16 v[108:111], v[128:131], v[200:203], v[108:111]
	v_mfma_f32_16x16x32_bf16 v[104:107], v[136:139], v[200:203], v[104:107]
	v_mfma_f32_16x16x32_bf16 v[100:103], v[128:131], v[208:211], v[100:103]
	v_mfma_f32_16x16x32_bf16 v[96:99], v[136:139], v[208:211], v[96:99]
	v_mfma_f32_16x16x32_bf16 v[124:127], v[132:135], v[164:167], v[124:127]
	v_mfma_f32_16x16x32_bf16 v[120:123], v[140:143], v[164:167], v[120:123]
	v_mfma_f32_16x16x32_bf16 v[116:119], v[132:135], v[172:175], v[116:119]
	v_mfma_f32_16x16x32_bf16 v[112:115], v[140:143], v[172:175], v[112:115]
	v_mfma_f32_16x16x32_bf16 v[108:111], v[132:135], v[204:207], v[108:111]
	v_mfma_f32_16x16x32_bf16 v[104:107], v[140:143], v[204:207], v[104:107]
	v_mfma_f32_16x16x32_bf16 v[100:103], v[132:135], v[212:215], v[100:103]
	v_mfma_f32_16x16x32_bf16 v[96:99], v[140:143], v[212:215], v[96:99]
	v_mfma_f32_16x16x32_bf16 v[92:95], v[144:147], v[160:163], v[92:95]
	v_mfma_f32_16x16x32_bf16 v[88:91], v[152:155], v[160:163], v[88:91]
	v_mfma_f32_16x16x32_bf16 v[84:87], v[144:147], v[168:171], v[84:87]
	v_mfma_f32_16x16x32_bf16 v[80:83], v[152:155], v[168:171], v[80:83]
	v_mfma_f32_16x16x32_bf16 v[76:79], v[144:147], v[200:203], v[76:79]
	v_mfma_f32_16x16x32_bf16 v[72:75], v[152:155], v[200:203], v[72:75]
	v_mfma_f32_16x16x32_bf16 v[68:71], v[144:147], v[208:211], v[68:71]
	v_mfma_f32_16x16x32_bf16 v[64:67], v[152:155], v[208:211], v[64:67]
	v_mfma_f32_16x16x32_bf16 v[92:95], v[148:151], v[164:167], v[92:95]
	v_mfma_f32_16x16x32_bf16 v[88:91], v[156:159], v[164:167], v[88:91]
	v_mfma_f32_16x16x32_bf16 v[84:87], v[148:151], v[172:175], v[84:87]
	v_mfma_f32_16x16x32_bf16 v[80:83], v[156:159], v[172:175], v[80:83]
	v_mfma_f32_16x16x32_bf16 v[76:79], v[148:151], v[204:207], v[76:79]
	v_mfma_f32_16x16x32_bf16 v[72:75], v[156:159], v[204:207], v[72:75]
	v_mfma_f32_16x16x32_bf16 v[68:71], v[148:151], v[212:215], v[68:71]
	v_mfma_f32_16x16x32_bf16 v[64:67], v[156:159], v[212:215], v[64:67]
	s_setprio 0
	s_barrier
; #define PG8_STAGE(bufoff, gbase, voff) do { _Pragma("unroll") for (int _i = 0; _i < 2; ++_i) \
;         __builtin_amdgcn_global_load_lds((const unsigned*)((const char*)(gbase) + (voff)[_i]), (LAS unsigned*)(lds + (bufoff) + ldsw + _i * 8192), 16, 0, 0); } while (0)
; #define PG8_LDA(dst, b, h) do { _Pragma("unroll") for (int m = 0; m < 4; ++m) _Pragma("unroll") for (int k = 0; k < 2; ++k) dst[m][k] = *(const LAS bf16x8*)(lds + PG8_SA(b, h) + aoff + m * 2048 + k * 1024); } while (0)
; #define PG8_WAIT_V(n) asm volatile("s_waitcnt vmcnt(" #n ")" ::: "memory")
; #define PG8_WAIT_L(n) asm volatile("s_waitcnt lgkmcnt(" #n ")" ::: "memory")
; #define PG8_BAR __builtin_amdgcn_s_barrier()
; #define PG8_SCHED __builtin_amdgcn_sched_barrier(0)
; template <class Epi, class Sched, bool F8 = false>
; __device__ __forceinline__ void gemm_phase(LAS unsigned char* lds, const Gemm g, const Sched& S, const Epi& E) {
;     ...
;             PG8_LDA(At, 1, 1); PG8_STAGE(PG8_SB(1, 0), b3, voffB); PG8_STAGE(PG8_SB(1, 1), b3 + hstepB, voffB); PG8_STAGE(PG8_SA(1, 0), a3, voffA);
;             PG8_WAIT_V(8); PG8_WAIT_L(0); PG8_BAR; PG8_MMA(1, 0, At, B0); PG8_MMA(1, 1, At, B1); PG8_BAR; PG8_SCHED;
;         }
;         if (wr == 0) PG8_BAR;
	s_add_i32 s36, s81, s38
	s_add_i32 m0, s36, 0xffffff80
	ds_read_b128 v[160:163], v199 offset:49152
	ds_read_b128 v[164:167], v199 offset:50176
	ds_read_b128 v[168:171], v199 offset:51200
	ds_read_b128 v[172:175], v199 offset:52224
	ds_read_b128 v[200:203], v199 offset:53248
	ds_read_b128 v[204:207], v199 offset:54272
	ds_read_b128 v[208:211], v199 offset:55296
	ds_read_b128 v[212:215], v199 offset:56320
	global_load_lds_dwordx4 v[216:217], off offset:128
	s_add_i32 m0, s36, 0x1f80
	s_add_u32 s34, s34, 0x80080
	s_addc_u32 s35, s35, 0
	s_add_i32 s36, s82, s38
	global_load_lds_dwordx4 v[218:219], off offset:128
	s_mov_b32 m0, s36
	s_nop 0
	global_load_lds_dwordx4 v180, s[34:35]
	s_add_i32 m0, s36, 0x2000
	s_nop 0
	global_load_lds_dwordx4 v176, s[34:35]
	s_add_i32 m0, s45, 0xffffff80
	s_nop 0
	global_load_lds_dwordx4 v[220:221], off offset:128
	s_add_i32 m0, s47, 0xffffff80
	s_nop 0
	global_load_lds_dwordx4 v[222:223], off offset:128
	s_waitcnt vmcnt(8)
	s_waitcnt lgkmcnt(0)
	s_barrier
	s_setprio 1
	s_waitcnt lgkmcnt(0)
	v_mfma_f32_16x16x32_bf16 v[60:63], v[128:131], v[160:163], v[60:63]
	v_mfma_f32_16x16x32_bf16 v[56:59], v[136:139], v[160:163], v[56:59]
	v_mfma_f32_16x16x32_bf16 v[52:55], v[128:131], v[168:171], v[52:55]
	v_mfma_f32_16x16x32_bf16 v[48:51], v[136:139], v[168:171], v[48:51]
	v_mfma_f32_16x16x32_bf16 v[44:47], v[128:131], v[200:203], v[44:47]
	v_mfma_f32_16x16x32_bf16 v[40:43], v[136:139], v[200:203], v[40:43]
	v_mfma_f32_16x16x32_bf16 v[36:39], v[128:131], v[208:211], v[36:39]
	v_mfma_f32_16x16x32_bf16 v[32:35], v[136:139], v[208:211], v[32:35]
	v_mfma_f32_16x16x32_bf16 v[60:63], v[132:135], v[164:167], v[60:63]
	v_mfma_f32_16x16x32_bf16 v[56:59], v[140:143], v[164:167], v[56:59]
	v_mfma_f32_16x16x32_bf16 v[52:55], v[132:135], v[172:175], v[52:55]
	v_mfma_f32_16x16x32_bf16 v[48:51], v[140:143], v[172:175], v[48:51]
	v_mfma_f32_16x16x32_bf16 v[44:47], v[132:135], v[204:207], v[44:47]
	v_mfma_f32_16x16x32_bf16 v[40:43], v[140:143], v[204:207], v[40:43]
	v_mfma_f32_16x16x32_bf16 v[36:39], v[132:135], v[212:215], v[36:39]
	v_mfma_f32_16x16x32_bf16 v[32:35], v[140:143], v[212:215], v[32:35]
	v_mfma_f32_16x16x32_bf16 v[28:31], v[144:147], v[160:163], v[28:31]
	v_mfma_f32_16x16x32_bf16 v[24:27], v[152:155], v[160:163], v[24:27]
	v_mfma_f32_16x16x32_bf16 v[20:23], v[144:147], v[168:171], v[20:23]
	v_mfma_f32_16x16x32_bf16 v[16:19], v[152:155], v[168:171], v[16:19]
	v_mfma_f32_16x16x32_bf16 v[12:15], v[144:147], v[200:203], v[12:15]
	v_mfma_f32_16x16x32_bf16 v[8:11], v[152:155], v[200:203], v[8:11]
	v_mfma_f32_16x16x32_bf16 v[4:7], v[144:147], v[208:211], v[4:7]
	v_mfma_f32_16x16x32_bf16 v[0:3], v[152:155], v[208:211], v[0:3]
	v_mfma_f32_16x16x32_bf16 v[28:31], v[148:151], v[164:167], v[28:31]
	v_mfma_f32_16x16x32_bf16 v[24:27], v[156:159], v[164:167], v[24:27]
	v_mfma_f32_16x16x32_bf16 v[20:23], v[148:151], v[172:175], v[20:23]
	v_mfma_f32_16x16x32_bf16 v[16:19], v[156:159], v[172:175], v[16:19]
	v_mfma_f32_16x16x32_bf16 v[12:15], v[148:151], v[204:207], v[12:15]
	v_mfma_f32_16x16x32_bf16 v[8:11], v[156:159], v[204:207], v[8:11]
	v_mfma_f32_16x16x32_bf16 v[4:7], v[148:151], v[212:215], v[4:7]
	v_mfma_f32_16x16x32_bf16 v[0:3], v[156:159], v[212:215], v[0:3]
	s_setprio 0
	s_barrier
	s_add_u32 s30, s30, 0x100
	s_addc_u32 s31, s31, 0
	s_add_u32 s78, s78, 0x100
	s_addc_u32 s79, s79, 0
	s_cmp_ge_i32 s80, s9
	s_mov_b32 s34, s80
	s_cbranch_scc0 .LBB0_753
	s_and_b64 vcc, exec, s[18:19]
	s_cbranch_vccz .LBB0_756
	s_barrier

; #define PG8_STAGE(bufoff, gbase, voff) do { _Pragma("unroll") for (int _i = 0; _i < 2; ++_i) \
;         __builtin_amdgcn_global_load_lds((const unsigned*)((const char*)(gbase) + (voff)[_i]), (LAS unsigned*)(lds + (bufoff) + ldsw + _i * 8192), 16, 0, 0); } while (0)
; #define PG8_LDA(dst, b, h) do { _Pragma("unroll") for (int m = 0; m < 4; ++m) _Pragma("unroll") for (int k = 0; k < 2; ++k) dst[m][k] = *(const LAS bf16x8*)(lds + PG8_SA(b, h) + aoff + m * 2048 + k * 1024); } while (0)
; #define PG8_LDB(dst, b, h) do { _Pragma("unroll") for (int n = 0; n < 2; ++n) _Pragma("unroll") for (int k = 0; k < 2; ++k) dst[n][k] = *(const LAS bf16x8*)(lds + PG8_SB(b, h) + boff + n * 2048 + k * 1024); } while (0)
; #define PG8_WAIT_V(n) asm volatile("s_waitcnt vmcnt(" #n ")" ::: "memory")
; #define PG8_WAIT_L(n) asm volatile("s_waitcnt lgkmcnt(" #n ")" ::: "memory")
; #define PG8_BAR __builtin_amdgcn_s_barrier()
; #define PG8_SCHED __builtin_amdgcn_sched_barrier(0)
; template <class Epi, class Sched, bool F8 = false>
; __device__ __forceinline__ void gemm_phase(LAS unsigned char* lds, const Gemm g, const Sched& S, const Epi& E) {
;     ...
;             const bool last = (t == nt - 2);
;             const char* a1 = cA + (size_t)(t + 1) * kstep;
;             const char* a2 = last ? nA : cA + (size_t)(t + 2) * kstep; const char* b2 = last ? nB : cB + (size_t)(t + 2) * kstep;
;             const char* a3 = a2 + kstep; const char* b3 = b2 + kstep;
;             PG8_LDB(B0, 0, 0); PG8_LDB(B1, 0, 1); PG8_SCHED; PG8_LDA(At, 0, 0); PG8_STAGE(PG8_SA(1, 1), a1 + hstepA, voffA);
;             PG8_WAIT_V(8); PG8_WAIT_L(0); PG8_BAR; PG8_MMA(0, 0, At, B0); PG8_MMA(0, 1, At, B1); PG8_BAR; PG8_SCHED;
;             PG8_LDA(At, 0, 1); PG8_STAGE(PG8_SB(0, 0), b2, voffB); PG8_STAGE(PG8_SB(0, 1), b2 + hstepB, voffB); PG8_STAGE(PG8_SA(0, 0), a2, voffA);
;             PG8_WAIT_V(8); PG8_WAIT_L(0); PG8_BAR; PG8_MMA(1, 0, At, B0); PG8_MMA(1, 1, At, B1); PG8_BAR; PG8_SCHED;
;             PG8_LDB(B0, 1, 0); PG8_LDB(B1, 1, 1); PG8_SCHED; PG8_LDA(At, 1, 0); PG8_STAGE(PG8_SA(0, 1), a2 + hstepA, voffA);
;             PG8_WAIT_V(8); PG8_WAIT_L(0); PG8_BAR; PG8_MMA(0, 0, At, B0); PG8_MMA(0, 1, At, B1); PG8_BAR; PG8_SCHED;
.LBB0_825:
	ds_read_b128 v[168:171], v164
	ds_read_b128 v[172:175], v164 offset:1024
	ds_read_b128 v[176:179], v164 offset:2048
	ds_read_b128 v[180:183], v164 offset:3072
	ds_read_b128 v[184:187], v165
	ds_read_b128 v[192:195], v165 offset:1024
	ds_read_b128 v[196:199], v165 offset:2048
	ds_read_b128 v[200:203], v165 offset:3072
	s_add_u32 s38, s36, 0xfff80080
	s_addc_u32 s39, s37, -1
	s_cmp_eq_u32 s58, 28
	s_cselect_b32 s41, s10, s39
	s_cselect_b32 s40, s27, s38
	s_cselect_b32 s39, s25, s57
	s_cselect_b32 s38, s35, s56
	s_add_i32 m0, s43, 0xc000
	ds_read_b128 v[204:207], v166
	ds_read_b128 v[208:211], v166 offset:1024
	ds_read_b128 v[212:215], v166 offset:2048
	ds_read_b128 v[216:219], v166 offset:3072
	ds_read_b128 v[220:223], v166 offset:4096
	ds_read_b128 v[224:227], v166 offset:5120
	ds_read_b128 v[228:231], v166 offset:6144
	ds_read_b128 v[232:235], v166 offset:7168
	global_load_lds_dwordx4 v152, s[36:37]
	s_add_i32 m0, s43, 0xe000
	s_nop 0
	global_load_lds_dwordx4 v154, s[36:37]
	s_waitcnt vmcnt(8)
	s_waitcnt lgkmcnt(0)
	s_barrier
	s_setprio 1
	s_waitcnt lgkmcnt(0)
	v_mfma_f32_16x16x32_bf16 v[124:127], v[168:171], v[204:207], v[124:127]
	v_mfma_f32_16x16x32_bf16 v[120:123], v[176:179], v[204:207], v[120:123]
	v_mfma_f32_16x16x32_bf16 v[116:119], v[168:171], v[212:215], v[116:119]
	v_mfma_f32_16x16x32_bf16 v[108:111], v[176:179], v[212:215], v[108:111]
	v_mfma_f32_16x16x32_bf16 v[100:103], v[168:171], v[220:223], v[100:103]
	v_mfma_f32_16x16x32_bf16 v[92:95], v[176:179], v[220:223], v[92:95]
	v_mfma_f32_16x16x32_bf16 v[84:87], v[168:171], v[228:231], v[84:87]
	v_mfma_f32_16x16x32_bf16 v[76:79], v[176:179], v[228:231], v[76:79]
	v_mfma_f32_16x16x32_bf16 v[124:127], v[172:175], v[208:211], v[124:127]
	v_mfma_f32_16x16x32_bf16 v[120:123], v[180:183], v[208:211], v[120:123]
	v_mfma_f32_16x16x32_bf16 v[116:119], v[172:175], v[216:219], v[116:119]
	v_mfma_f32_16x16x32_bf16 v[108:111], v[180:183], v[216:219], v[108:111]
	v_mfma_f32_16x16x32_bf16 v[100:103], v[172:175], v[224:227], v[100:103]
	v_mfma_f32_16x16x32_bf16 v[92:95], v[180:183], v[224:227], v[92:95]
	v_mfma_f32_16x16x32_bf16 v[84:87], v[172:175], v[232:235], v[84:87]
	v_mfma_f32_16x16x32_bf16 v[76:79], v[180:183], v[232:235], v[76:79]
	v_mfma_f32_16x16x32_bf16 v[112:115], v[184:187], v[204:207], v[112:115]
	v_mfma_f32_16x16x32_bf16 v[104:107], v[196:199], v[204:207], v[104:107]
	v_mfma_f32_16x16x32_bf16 v[96:99], v[184:187], v[212:215], v[96:99]
	v_mfma_f32_16x16x32_bf16 v[88:91], v[196:199], v[212:215], v[88:91]
	v_mfma_f32_16x16x32_bf16 v[80:83], v[184:187], v[220:223], v[80:83]
	v_mfma_f32_16x16x32_bf16 v[72:75], v[196:199], v[220:223], v[72:75]
	v_mfma_f32_16x16x32_bf16 v[68:71], v[184:187], v[228:231], v[68:71]
	v_mfma_f32_16x16x32_bf16 v[64:67], v[196:199], v[228:231], v[64:67]
	v_mfma_f32_16x16x32_bf16 v[112:115], v[192:195], v[208:211], v[112:115]
	v_mfma_f32_16x16x32_bf16 v[104:107], v[200:203], v[208:211], v[104:107]
	v_mfma_f32_16x16x32_bf16 v[96:99], v[192:195], v[216:219], v[96:99]
	v_mfma_f32_16x16x32_bf16 v[88:91], v[200:203], v[216:219], v[88:91]
	v_mfma_f32_16x16x32_bf16 v[80:83], v[192:195], v[224:227], v[80:83]
	v_mfma_f32_16x16x32_bf16 v[72:75], v[200:203], v[224:227], v[72:75]
	v_mfma_f32_16x16x32_bf16 v[68:71], v[192:195], v[232:235], v[68:71]
	v_mfma_f32_16x16x32_bf16 v[64:67], v[200:203], v[232:235], v[64:67]
	s_setprio 0
	s_barrier
	s_add_i32 s59, s50, s23
	v_lshl_add_u64 v[160:161], s[38:39], 0, v[132:133]
	s_mov_b32 m0, s59
	ds_read_b128 v[204:207], v166 offset:16384
	ds_read_b128 v[208:211], v166 offset:17408
	ds_read_b128 v[212:215], v166 offset:18432
	ds_read_b128 v[216:219], v166 offset:19456
	ds_read_b128 v[220:223], v166 offset:20480
	ds_read_b128 v[224:227], v166 offset:21504
	ds_read_b128 v[228:231], v166 offset:22528
	ds_read_b128 v[232:235], v166 offset:23552
	global_load_lds_dwordx4 v[160:161], off
	s_add_i32 m0, s59, 0x2000
	s_add_u32 s72, s38, 0x80000
	v_lshl_add_u64 v[188:189], s[38:39], 0, v[128:129]
	s_addc_u32 s73, s39, 0
	s_add_i32 s59, s91, s23
	global_load_lds_dwordx4 v[188:189], off
	s_mov_b32 m0, s59
	v_lshl_add_u64 v[238:239], s[40:41], 0, v[130:131]
	global_load_lds_dwordx4 v132, s[72:73]
	s_add_i32 m0, s59, 0x2000
	s_nop 0
	global_load_lds_dwordx4 v128, s[72:73]
	v_lshl_add_u64 v[236:237], s[40:41], 0, v[134:135]
	s_mov_b32 m0, s43
	s_nop 0
	global_load_lds_dwordx4 v[236:237], off
	s_mov_b32 m0, s44
	s_nop 0
	global_load_lds_dwordx4 v[238:239], off
	s_waitcnt vmcnt(8)
	s_waitcnt lgkmcnt(0)
	s_barrier
	s_setprio 1
	s_waitcnt lgkmcnt(0)
	v_mfma_f32_16x16x32_bf16 v[60:63], v[168:171], v[204:207], v[60:63]
	v_mfma_f32_16x16x32_bf16 v[56:59], v[176:179], v[204:207], v[56:59]
	v_mfma_f32_16x16x32_bf16 v[52:55], v[168:171], v[212:215], v[52:55]
	v_mfma_f32_16x16x32_bf16 v[44:47], v[176:179], v[212:215], v[44:47]
	v_mfma_f32_16x16x32_bf16 v[36:39], v[168:171], v[220:223], v[36:39]
	v_mfma_f32_16x16x32_bf16 v[28:31], v[176:179], v[220:223], v[28:31]
	v_mfma_f32_16x16x32_bf16 v[20:23], v[168:171], v[228:231], v[20:23]
	v_mfma_f32_16x16x32_bf16 v[12:15], v[176:179], v[228:231], v[12:15]
	v_mfma_f32_16x16x32_bf16 v[60:63], v[172:175], v[208:211], v[60:63]
	v_mfma_f32_16x16x32_bf16 v[56:59], v[180:183], v[208:211], v[56:59]
	v_mfma_f32_16x16x32_bf16 v[52:55], v[172:175], v[216:219], v[52:55]
	v_mfma_f32_16x16x32_bf16 v[44:47], v[180:183], v[216:219], v[44:47]
	v_mfma_f32_16x16x32_bf16 v[36:39], v[172:175], v[224:227], v[36:39]
	v_mfma_f32_16x16x32_bf16 v[28:31], v[180:183], v[224:227], v[28:31]
	v_mfma_f32_16x16x32_bf16 v[20:23], v[172:175], v[232:235], v[20:23]
	v_mfma_f32_16x16x32_bf16 v[12:15], v[180:183], v[232:235], v[12:15]
	v_mfma_f32_16x16x32_bf16 v[48:51], v[184:187], v[204:207], v[48:51]
	v_mfma_f32_16x16x32_bf16 v[40:43], v[196:199], v[204:207], v[40:43]
	v_mfma_f32_16x16x32_bf16 v[32:35], v[184:187], v[212:215], v[32:35]
	v_mfma_f32_16x16x32_bf16 v[24:27], v[196:199], v[212:215], v[24:27]
	v_mfma_f32_16x16x32_bf16 v[16:19], v[184:187], v[220:223], v[16:19]
	v_mfma_f32_16x16x32_bf16 v[8:11], v[196:199], v[220:223], v[8:11]
	v_mfma_f32_16x16x32_bf16 v[4:7], v[184:187], v[228:231], v[4:7]
	v_mfma_f32_16x16x32_bf16 v[0:3], v[196:199], v[228:231], v[0:3]
	v_mfma_f32_16x16x32_bf16 v[48:51], v[192:195], v[208:211], v[48:51]
	v_mfma_f32_16x16x32_bf16 v[40:43], v[200:203], v[208:211], v[40:43]
	v_mfma_f32_16x16x32_bf16 v[32:35], v[192:195], v[216:219], v[32:35]
	v_mfma_f32_16x16x32_bf16 v[24:27], v[200:203], v[216:219], v[24:27]
	v_mfma_f32_16x16x32_bf16 v[16:19], v[192:195], v[224:227], v[16:19]
	v_mfma_f32_16x16x32_bf16 v[8:11], v[200:203], v[224:227], v[8:11]
	v_mfma_f32_16x16x32_bf16 v[4:7], v[192:195], v[232:235], v[4:7]
	v_mfma_f32_16x16x32_bf16 v[0:3], v[200:203], v[232:235], v[0:3]
	s_setprio 0
	s_barrier
; #define PG8_STAGE(bufoff, gbase, voff) do { _Pragma("unroll") for (int _i = 0; _i < 2; ++_i) \
;         __builtin_amdgcn_global_load_lds((const unsigned*)((const char*)(gbase) + (voff)[_i]), (LAS unsigned*)(lds + (bufoff) + ldsw + _i * 8192), 16, 0, 0); } while (0)
; #define PG8_LDA(dst, b, h) do { _Pragma("unroll") for (int m = 0; m < 4; ++m) _Pragma("unroll") for (int k = 0; k < 2; ++k) dst[m][k] = *(const LAS bf16x8*)(lds + PG8_SA(b, h) + aoff + m * 2048 + k * 1024); } while (0)
; #define PG8_WAIT_V(n) asm volatile("s_waitcnt vmcnt(" #n ")" ::: "memory")
; #define PG8_WAIT_L(n) asm volatile("s_waitcnt lgkmcnt(" #n ")" ::: "memory")
; #define PG8_BAR __builtin_amdgcn_s_barrier()
; #define PG8_SCHED __builtin_amdgcn_sched_barrier(0)
; template <class Epi, class Sched, bool F8 = false>
; __device__ __forceinline__ void gemm_phase(LAS unsigned char* lds, const Gemm g, const Sched& S, const Epi& E) {
;     ...
;             PG8_WAIT_V(8); PG8_WAIT_L(0); PG8_BAR; PG8_MMA(0, 0, At, B0); PG8_MMA(0, 1, At, B1); PG8_BAR; PG8_SCHED;
;             PG8_LDA(At, 1, 1); PG8_STAGE(PG8_SB(1, 0), b3, voffB); PG8_STAGE(PG8_SB(1, 1), b3 + hstepB, voffB); PG8_STAGE(PG8_SA(1, 0), a3, voffA);
;             PG8_WAIT_V(8); PG8_WAIT_L(0); PG8_BAR; PG8_MMA(1, 0, At, B0); PG8_MMA(1, 1, At, B1); PG8_BAR; PG8_SCHED;
;         }
;         if (wr == 0) PG8_BAR;
	s_add_i32 s59, 0, 0x18000
	v_add_u32_e32 v167, s59, v162
	s_add_i32 s72, 0, 0x1c000
	ds_read_b128 v[168:171], v167
	ds_read_b128 v[172:175], v167 offset:1024
	ds_read_b128 v[176:179], v167 offset:2048
	ds_read_b128 v[180:183], v167 offset:3072
	v_add_u32_e32 v167, s72, v162
	ds_read_b128 v[184:187], v167
	ds_read_b128 v[192:195], v167 offset:1024
	ds_read_b128 v[196:199], v167 offset:2048
	ds_read_b128 v[200:203], v167 offset:3072
	s_add_u32 s40, s40, 0x80000
	s_addc_u32 s41, s41, 0
	s_mov_b32 m0, s45
	ds_read_b128 v[204:207], v166 offset:32768
	ds_read_b128 v[208:211], v166 offset:33792
	ds_read_b128 v[212:215], v166 offset:34816
	ds_read_b128 v[216:219], v166 offset:35840
	ds_read_b128 v[220:223], v166 offset:36864
	ds_read_b128 v[224:227], v166 offset:37888
	ds_read_b128 v[228:231], v166 offset:38912
	ds_read_b128 v[232:235], v166 offset:39936
	global_load_lds_dwordx4 v134, s[40:41]
	s_mov_b32 m0, s47
	s_nop 0
	global_load_lds_dwordx4 v130, s[40:41]
	s_waitcnt vmcnt(8)
	s_waitcnt lgkmcnt(0)
	s_barrier
	s_setprio 1
	s_waitcnt lgkmcnt(0)
	v_mfma_f32_16x16x32_bf16 v[124:127], v[168:171], v[204:207], v[124:127]
	v_mfma_f32_16x16x32_bf16 v[120:123], v[176:179], v[204:207], v[120:123]
	v_mfma_f32_16x16x32_bf16 v[116:119], v[168:171], v[212:215], v[116:119]
	v_mfma_f32_16x16x32_bf16 v[108:111], v[176:179], v[212:215], v[108:111]
	v_mfma_f32_16x16x32_bf16 v[100:103], v[168:171], v[220:223], v[100:103]
	v_mfma_f32_16x16x32_bf16 v[92:95], v[176:179], v[220:223], v[92:95]
	v_mfma_f32_16x16x32_bf16 v[84:87], v[168:171], v[228:231], v[84:87]
	v_mfma_f32_16x16x32_bf16 v[76:79], v[176:179], v[228:231], v[76:79]
	v_mfma_f32_16x16x32_bf16 v[124:127], v[172:175], v[208:211], v[124:127]
	v_mfma_f32_16x16x32_bf16 v[120:123], v[180:183], v[208:211], v[120:123]
	v_mfma_f32_16x16x32_bf16 v[116:119], v[172:175], v[216:219], v[116:119]
	v_mfma_f32_16x16x32_bf16 v[108:111], v[180:183], v[216:219], v[108:111]
	v_mfma_f32_16x16x32_bf16 v[100:103], v[172:175], v[224:227], v[100:103]
	v_mfma_f32_16x16x32_bf16 v[92:95], v[180:183], v[224:227], v[92:95]
	v_mfma_f32_16x16x32_bf16 v[84:87], v[172:175], v[232:235], v[84:87]
	v_mfma_f32_16x16x32_bf16 v[76:79], v[180:183], v[232:235], v[76:79]
	v_mfma_f32_16x16x32_bf16 v[112:115], v[184:187], v[204:207], v[112:115]
	v_mfma_f32_16x16x32_bf16 v[104:107], v[196:199], v[204:207], v[104:107]
	v_mfma_f32_16x16x32_bf16 v[96:99], v[184:187], v[212:215], v[96:99]
	v_mfma_f32_16x16x32_bf16 v[88:91], v[196:199], v[212:215], v[88:91]
	v_mfma_f32_16x16x32_bf16 v[80:83], v[184:187], v[220:223], v[80:83]
	v_mfma_f32_16x16x32_bf16 v[72:75], v[196:199], v[220:223], v[72:75]
	v_mfma_f32_16x16x32_bf16 v[68:71], v[184:187], v[228:231], v[68:71]
	v_mfma_f32_16x16x32_bf16 v[64:67], v[196:199], v[228:231], v[64:67]
	v_mfma_f32_16x16x32_bf16 v[112:115], v[192:195], v[208:211], v[112:115]
	v_mfma_f32_16x16x32_bf16 v[104:107], v[200:203], v[208:211], v[104:107]
	v_mfma_f32_16x16x32_bf16 v[96:99], v[192:195], v[216:219], v[96:99]
	v_mfma_f32_16x16x32_bf16 v[88:91], v[200:203], v[216:219], v[88:91]
	v_mfma_f32_16x16x32_bf16 v[80:83], v[192:195], v[224:227], v[80:83]
	v_mfma_f32_16x16x32_bf16 v[72:75], v[200:203], v[224:227], v[72:75]
	v_mfma_f32_16x16x32_bf16 v[68:71], v[192:195], v[232:235], v[68:71]
	v_mfma_f32_16x16x32_bf16 v[64:67], v[200:203], v[232:235], v[64:67]
	s_setprio 0
	s_barrier
	s_add_i32 s40, s59, s23
	s_add_i32 m0, s40, 0xffffff80
	ds_read_b128 v[204:207], v166 offset:49152
	ds_read_b128 v[208:211], v166 offset:50176
	ds_read_b128 v[212:215], v166 offset:51200
	ds_read_b128 v[216:219], v166 offset:52224
	ds_read_b128 v[220:223], v166 offset:53248
	ds_read_b128 v[224:227], v166 offset:54272
	ds_read_b128 v[228:231], v166 offset:55296
	ds_read_b128 v[232:235], v166 offset:56320
	global_load_lds_dwordx4 v[160:161], off offset:128
	s_add_i32 m0, s40, 0x1f80
	s_add_u32 s38, s38, 0x80080
	s_addc_u32 s39, s39, 0
	s_add_i32 s40, s72, s23
	global_load_lds_dwordx4 v[188:189], off offset:128
	s_mov_b32 m0, s40
	s_nop 0
	global_load_lds_dwordx4 v132, s[38:39]
	s_add_i32 m0, s40, 0x2000
	s_nop 0
	global_load_lds_dwordx4 v128, s[38:39]
	s_add_i32 m0, s48, 0xffffff80
	s_nop 0
	global_load_lds_dwordx4 v[236:237], off offset:128
	s_add_i32 m0, s49, 0xffffff80
	s_nop 0
	global_load_lds_dwordx4 v[238:239], off offset:128
	s_waitcnt vmcnt(8)
	s_waitcnt lgkmcnt(0)
	s_barrier
	s_setprio 1
	s_waitcnt lgkmcnt(0)
	v_mfma_f32_16x16x32_bf16 v[60:63], v[168:171], v[204:207], v[60:63]
	v_mfma_f32_16x16x32_bf16 v[56:59], v[176:179], v[204:207], v[56:59]
	v_mfma_f32_16x16x32_bf16 v[52:55], v[168:171], v[212:215], v[52:55]
	v_mfma_f32_16x16x32_bf16 v[44:47], v[176:179], v[212:215], v[44:47]
	v_mfma_f32_16x16x32_bf16 v[36:39], v[168:171], v[220:223], v[36:39]
	v_mfma_f32_16x16x32_bf16 v[28:31], v[176:179], v[220:223], v[28:31]
	v_mfma_f32_16x16x32_bf16 v[20:23], v[168:171], v[228:231], v[20:23]
	v_mfma_f32_16x16x32_bf16 v[12:15], v[176:179], v[228:231], v[12:15]
	v_mfma_f32_16x16x32_bf16 v[60:63], v[172:175], v[208:211], v[60:63]
	v_mfma_f32_16x16x32_bf16 v[56:59], v[180:183], v[208:211], v[56:59]
	v_mfma_f32_16x16x32_bf16 v[52:55], v[172:175], v[216:219], v[52:55]
	v_mfma_f32_16x16x32_bf16 v[44:47], v[180:183], v[216:219], v[44:47]
	v_mfma_f32_16x16x32_bf16 v[36:39], v[172:175], v[224:227], v[36:39]
	v_mfma_f32_16x16x32_bf16 v[28:31], v[180:183], v[224:227], v[28:31]
	v_mfma_f32_16x16x32_bf16 v[20:23], v[172:175], v[232:235], v[20:23]
	v_mfma_f32_16x16x32_bf16 v[12:15], v[180:183], v[232:235], v[12:15]
	v_mfma_f32_16x16x32_bf16 v[48:51], v[184:187], v[204:207], v[48:51]
	v_mfma_f32_16x16x32_bf16 v[40:43], v[196:199], v[204:207], v[40:43]
	v_mfma_f32_16x16x32_bf16 v[32:35], v[184:187], v[212:215], v[32:35]
	v_mfma_f32_16x16x32_bf16 v[24:27], v[196:199], v[212:215], v[24:27]
	v_mfma_f32_16x16x32_bf16 v[16:19], v[184:187], v[220:223], v[16:19]
	v_mfma_f32_16x16x32_bf16 v[8:11], v[196:199], v[220:223], v[8:11]
	v_mfma_f32_16x16x32_bf16 v[4:7], v[184:187], v[228:231], v[4:7]
	v_mfma_f32_16x16x32_bf16 v[0:3], v[196:199], v[228:231], v[0:3]
	v_mfma_f32_16x16x32_bf16 v[48:51], v[192:195], v[208:211], v[48:51]
	v_mfma_f32_16x16x32_bf16 v[40:43], v[200:203], v[208:211], v[40:43]
	v_mfma_f32_16x16x32_bf16 v[32:35], v[192:195], v[216:219], v[32:35]
	v_mfma_f32_16x16x32_bf16 v[24:27], v[200:203], v[216:219], v[24:27]
	v_mfma_f32_16x16x32_bf16 v[16:19], v[192:195], v[224:227], v[16:19]
	v_mfma_f32_16x16x32_bf16 v[8:11], v[200:203], v[224:227], v[8:11]
	v_mfma_f32_16x16x32_bf16 v[4:7], v[192:195], v[232:235], v[4:7]
	v_mfma_f32_16x16x32_bf16 v[0:3], v[200:203], v[232:235], v[0:3]
	s_setprio 0
	s_barrier
	s_add_i32 s58, s58, 2
	s_add_u32 s36, s36, 0x100
	s_addc_u32 s37, s37, 0
	s_add_u32 s56, s56, 0x100
	s_addc_u32 s57, s57, 0
	s_cmp_gt_u32 s58, 29
	s_cbranch_scc0 .LBB0_825
	s_and_b64 vcc, exec, s[20:21]
	s_cbranch_vccz .LBB0_828
	s_barrier

; #define PG8_STAGE(bufoff, gbase, voff) do { _Pragma("unroll") for (int _i = 0; _i < 2; ++_i) \
;         __builtin_amdgcn_global_load_lds((const unsigned*)((const char*)(gbase) + (voff)[_i]), (LAS unsigned*)(lds + (bufoff) + ldsw + _i * 8192), 16, 0, 0); } while (0)
; #define PG8_LDA(dst, b, h) do { _Pragma("unroll") for (int m = 0; m < 4; ++m) _Pragma("unroll") for (int k = 0; k < 2; ++k) dst[m][k] = *(const LAS bf16x8*)(lds + PG8_SA(b, h) + aoff + m * 2048 + k * 1024); } while (0)
; #define PG8_LDB(dst, b, h) do { _Pragma("unroll") for (int n = 0; n < 2; ++n) _Pragma("unroll") for (int k = 0; k < 2; ++k) dst[n][k] = *(const LAS bf16x8*)(lds + PG8_SB(b, h) + boff + n * 2048 + k * 1024); } while (0)
; #define PG8_WAIT_V(n) asm volatile("s_waitcnt vmcnt(" #n ")" ::: "memory")
; #define PG8_WAIT_L(n) asm volatile("s_waitcnt lgkmcnt(" #n ")" ::: "memory")
; #define PG8_BAR __builtin_amdgcn_s_barrier()
; #define PG8_SCHED __builtin_amdgcn_sched_barrier(0)
; template <class Epi, class Sched, bool F8 = false>
; __device__ __forceinline__ void gemm_phase(LAS unsigned char* lds, const Gemm g, const Sched& S, const Epi& E) {
;     ...
;             const bool last = (t == nt - 2);
;             const char* a1 = cA + (size_t)(t + 1) * kstep;
;             const char* a2 = last ? nA : cA + (size_t)(t + 2) * kstep; const char* b2 = last ? nB : cB + (size_t)(t + 2) * kstep;
;             const char* a3 = a2 + kstep; const char* b3 = b2 + kstep;
;             PG8_LDB(B0, 0, 0); PG8_LDB(B1, 0, 1); PG8_SCHED; PG8_LDA(At, 0, 0); PG8_STAGE(PG8_SA(1, 1), a1 + hstepA, voffA);
;             PG8_WAIT_V(8); PG8_WAIT_L(0); PG8_BAR; PG8_MMA(0, 0, At, B0); PG8_MMA(0, 1, At, B1); PG8_BAR; PG8_SCHED;
;             PG8_LDA(At, 0, 1); PG8_STAGE(PG8_SB(0, 0), b2, voffB); PG8_STAGE(PG8_SB(0, 1), b2 + hstepB, voffB); PG8_STAGE(PG8_SA(0, 0), a2, voffA);
;             PG8_WAIT_V(8); PG8_WAIT_L(0); PG8_BAR; PG8_MMA(1, 0, At, B0); PG8_MMA(1, 1, At, B1); PG8_BAR; PG8_SCHED;
;             PG8_LDB(B0, 1, 0); PG8_LDB(B1, 1, 1); PG8_SCHED; PG8_LDA(At, 1, 0); PG8_STAGE(PG8_SA(0, 1), a2 + hstepA, voffA);
;             PG8_WAIT_V(8); PG8_WAIT_L(0); PG8_BAR; PG8_MMA(0, 0, At, B0); PG8_MMA(0, 1, At, B1); PG8_BAR; PG8_SCHED;
.LBB0_954:
	ds_read_b128 v[150:153], v147
	ds_read_b128 v[154:157], v147 offset:1024
	ds_read_b128 v[158:161], v147 offset:2048
	ds_read_b128 v[162:165], v147 offset:3072
	ds_read_b128 v[166:169], v148
	ds_read_b128 v[170:173], v148 offset:1024
	ds_read_b128 v[174:177], v148 offset:2048
	ds_read_b128 v[178:181], v148 offset:3072
	s_add_u32 s30, s28, 0xfff80080
	s_addc_u32 s31, s29, -1
	s_cmp_eq_u32 s53, 28
	s_cselect_b32 s35, s21, s31
	s_cselect_b32 s34, s48, s30
	s_cselect_b32 s31, s19, s51
	s_cselect_b32 s30, s49, s50
	s_add_i32 m0, s27, 0xc000
	ds_read_b128 v[182:185], v149
	ds_read_b128 v[186:189], v149 offset:1024
	ds_read_b128 v[192:195], v149 offset:2048
	ds_read_b128 v[196:199], v149 offset:3072
	ds_read_b128 v[200:203], v149 offset:4096
	ds_read_b128 v[204:207], v149 offset:5120
	ds_read_b128 v[208:211], v149 offset:6144
	ds_read_b128 v[212:215], v149 offset:7168
	global_load_lds_dwordx4 v136, s[28:29]
	s_add_i32 m0, s27, 0xe000
	s_nop 0
	global_load_lds_dwordx4 v138, s[28:29]
	s_waitcnt vmcnt(8)
	s_waitcnt lgkmcnt(0)
	s_barrier
	s_setprio 1
	s_waitcnt lgkmcnt(0)
	v_mfma_f32_16x16x32_bf16 v[124:127], v[150:153], v[182:185], v[124:127]
	v_mfma_f32_16x16x32_bf16 v[120:123], v[158:161], v[182:185], v[120:123]
	v_mfma_f32_16x16x32_bf16 v[108:111], v[150:153], v[192:195], v[108:111]
	v_mfma_f32_16x16x32_bf16 v[104:107], v[158:161], v[192:195], v[104:107]
	v_mfma_f32_16x16x32_bf16 v[92:95], v[150:153], v[200:203], v[92:95]
	v_mfma_f32_16x16x32_bf16 v[88:91], v[158:161], v[200:203], v[88:91]
	v_mfma_f32_16x16x32_bf16 v[76:79], v[150:153], v[208:211], v[76:79]
	v_mfma_f32_16x16x32_bf16 v[72:75], v[158:161], v[208:211], v[72:75]
	v_mfma_f32_16x16x32_bf16 v[124:127], v[154:157], v[186:189], v[124:127]
	v_mfma_f32_16x16x32_bf16 v[120:123], v[162:165], v[186:189], v[120:123]
	v_mfma_f32_16x16x32_bf16 v[108:111], v[154:157], v[196:199], v[108:111]
	v_mfma_f32_16x16x32_bf16 v[104:107], v[162:165], v[196:199], v[104:107]
	v_mfma_f32_16x16x32_bf16 v[92:95], v[154:157], v[204:207], v[92:95]
	v_mfma_f32_16x16x32_bf16 v[88:91], v[162:165], v[204:207], v[88:91]
	v_mfma_f32_16x16x32_bf16 v[76:79], v[154:157], v[212:215], v[76:79]
	v_mfma_f32_16x16x32_bf16 v[72:75], v[162:165], v[212:215], v[72:75]
	v_mfma_f32_16x16x32_bf16 v[116:119], v[166:169], v[182:185], v[116:119]
	v_mfma_f32_16x16x32_bf16 v[112:115], v[174:177], v[182:185], v[112:115]
	v_mfma_f32_16x16x32_bf16 v[100:103], v[166:169], v[192:195], v[100:103]
	v_mfma_f32_16x16x32_bf16 v[96:99], v[174:177], v[192:195], v[96:99]
	v_mfma_f32_16x16x32_bf16 v[84:87], v[166:169], v[200:203], v[84:87]
	v_mfma_f32_16x16x32_bf16 v[80:83], v[174:177], v[200:203], v[80:83]
	v_mfma_f32_16x16x32_bf16 v[68:71], v[166:169], v[208:211], v[68:71]
	v_mfma_f32_16x16x32_bf16 v[64:67], v[174:177], v[208:211], v[64:67]
	v_mfma_f32_16x16x32_bf16 v[116:119], v[170:173], v[186:189], v[116:119]
	v_mfma_f32_16x16x32_bf16 v[112:115], v[178:181], v[186:189], v[112:115]
	v_mfma_f32_16x16x32_bf16 v[100:103], v[170:173], v[196:199], v[100:103]
	v_mfma_f32_16x16x32_bf16 v[96:99], v[178:181], v[196:199], v[96:99]
	v_mfma_f32_16x16x32_bf16 v[84:87], v[170:173], v[204:207], v[84:87]
	v_mfma_f32_16x16x32_bf16 v[80:83], v[178:181], v[204:207], v[80:83]
	v_mfma_f32_16x16x32_bf16 v[68:71], v[170:173], v[212:215], v[68:71]
	v_mfma_f32_16x16x32_bf16 v[64:67], v[178:181], v[212:215], v[64:67]
	s_setprio 0
	s_barrier
	s_add_i32 s56, s44, s36
	v_lshl_add_u64 v[216:217], s[30:31], 0, v[132:133]
	s_mov_b32 m0, s56
	ds_read_b128 v[182:185], v149 offset:16384
	ds_read_b128 v[186:189], v149 offset:17408
	ds_read_b128 v[192:195], v149 offset:18432
	ds_read_b128 v[196:199], v149 offset:19456
	ds_read_b128 v[200:203], v149 offset:20480
	ds_read_b128 v[204:207], v149 offset:21504
	ds_read_b128 v[208:211], v149 offset:22528
	ds_read_b128 v[212:215], v149 offset:23552
	global_load_lds_dwordx4 v[216:217], off
	s_add_i32 m0, s56, 0x2000
	s_add_u32 s56, s30, 0x80000
	v_lshl_add_u64 v[218:219], s[30:31], 0, v[128:129]
	s_addc_u32 s57, s31, 0
	s_add_i32 s58, s91, s36
	global_load_lds_dwordx4 v[218:219], off
	s_mov_b32 m0, s58
	v_lshl_add_u64 v[222:223], s[34:35], 0, v[130:131]
	global_load_lds_dwordx4 v132, s[56:57]
	s_add_i32 m0, s58, 0x2000
	s_nop 0
	global_load_lds_dwordx4 v128, s[56:57]
	v_lshl_add_u64 v[220:221], s[34:35], 0, v[134:135]
	s_mov_b32 m0, s27
	s_nop 0
	global_load_lds_dwordx4 v[220:221], off
	s_mov_b32 m0, s38
	s_nop 0
	global_load_lds_dwordx4 v[222:223], off
	s_waitcnt vmcnt(8)
	s_waitcnt lgkmcnt(0)
	s_barrier
	s_setprio 1
	s_waitcnt lgkmcnt(0)
	v_mfma_f32_16x16x32_bf16 v[60:63], v[150:153], v[182:185], v[60:63]
	v_mfma_f32_16x16x32_bf16 v[56:59], v[158:161], v[182:185], v[56:59]
	v_mfma_f32_16x16x32_bf16 v[44:47], v[150:153], v[192:195], v[44:47]
	v_mfma_f32_16x16x32_bf16 v[40:43], v[158:161], v[192:195], v[40:43]
	v_mfma_f32_16x16x32_bf16 v[28:31], v[150:153], v[200:203], v[28:31]
	v_mfma_f32_16x16x32_bf16 v[24:27], v[158:161], v[200:203], v[24:27]
	v_mfma_f32_16x16x32_bf16 v[12:15], v[150:153], v[208:211], v[12:15]
	v_mfma_f32_16x16x32_bf16 v[8:11], v[158:161], v[208:211], v[8:11]
	v_mfma_f32_16x16x32_bf16 v[60:63], v[154:157], v[186:189], v[60:63]
	v_mfma_f32_16x16x32_bf16 v[56:59], v[162:165], v[186:189], v[56:59]
	v_mfma_f32_16x16x32_bf16 v[44:47], v[154:157], v[196:199], v[44:47]
	v_mfma_f32_16x16x32_bf16 v[40:43], v[162:165], v[196:199], v[40:43]
	v_mfma_f32_16x16x32_bf16 v[28:31], v[154:157], v[204:207], v[28:31]
	v_mfma_f32_16x16x32_bf16 v[24:27], v[162:165], v[204:207], v[24:27]
	v_mfma_f32_16x16x32_bf16 v[12:15], v[154:157], v[212:215], v[12:15]
	v_mfma_f32_16x16x32_bf16 v[8:11], v[162:165], v[212:215], v[8:11]
	v_mfma_f32_16x16x32_bf16 v[52:55], v[166:169], v[182:185], v[52:55]
	v_mfma_f32_16x16x32_bf16 v[48:51], v[174:177], v[182:185], v[48:51]
	v_mfma_f32_16x16x32_bf16 v[36:39], v[166:169], v[192:195], v[36:39]
	v_mfma_f32_16x16x32_bf16 v[32:35], v[174:177], v[192:195], v[32:35]
	v_mfma_f32_16x16x32_bf16 v[20:23], v[166:169], v[200:203], v[20:23]
	v_mfma_f32_16x16x32_bf16 v[16:19], v[174:177], v[200:203], v[16:19]
	v_mfma_f32_16x16x32_bf16 v[4:7], v[166:169], v[208:211], v[4:7]
	v_mfma_f32_16x16x32_bf16 v[0:3], v[174:177], v[208:211], v[0:3]
	v_mfma_f32_16x16x32_bf16 v[52:55], v[170:173], v[186:189], v[52:55]
	v_mfma_f32_16x16x32_bf16 v[48:51], v[178:181], v[186:189], v[48:51]
	v_mfma_f32_16x16x32_bf16 v[36:39], v[170:173], v[196:199], v[36:39]
	v_mfma_f32_16x16x32_bf16 v[32:35], v[178:181], v[196:199], v[32:35]
	v_mfma_f32_16x16x32_bf16 v[20:23], v[170:173], v[204:207], v[20:23]
	v_mfma_f32_16x16x32_bf16 v[16:19], v[178:181], v[204:207], v[16:19]
	v_mfma_f32_16x16x32_bf16 v[4:7], v[170:173], v[212:215], v[4:7]
	v_mfma_f32_16x16x32_bf16 v[0:3], v[178:181], v[212:215], v[0:3]
	s_setprio 0
	s_barrier
; #define PG8_STAGE(bufoff, gbase, voff) do { _Pragma("unroll") for (int _i = 0; _i < 2; ++_i) \
;         __builtin_amdgcn_global_load_lds((const unsigned*)((const char*)(gbase) + (voff)[_i]), (LAS unsigned*)(lds + (bufoff) + ldsw + _i * 8192), 16, 0, 0); } while (0)
; #define PG8_LDA(dst, b, h) do { _Pragma("unroll") for (int m = 0; m < 4; ++m) _Pragma("unroll") for (int k = 0; k < 2; ++k) dst[m][k] = *(const LAS bf16x8*)(lds + PG8_SA(b, h) + aoff + m * 2048 + k * 1024); } while (0)
; #define PG8_WAIT_V(n) asm volatile("s_waitcnt vmcnt(" #n ")" ::: "memory")
; #define PG8_WAIT_L(n) asm volatile("s_waitcnt lgkmcnt(" #n ")" ::: "memory")
; #define PG8_BAR __builtin_amdgcn_s_barrier()
; #define PG8_SCHED __builtin_amdgcn_sched_barrier(0)
; template <class Epi, class Sched, bool F8 = false>
; __device__ __forceinline__ void gemm_phase(LAS unsigned char* lds, const Gemm g, const Sched& S, const Epi& E) {
;     ...
;             PG8_WAIT_V(8); PG8_WAIT_L(0); PG8_BAR; PG8_MMA(0, 0, At, B0); PG8_MMA(0, 1, At, B1); PG8_BAR; PG8_SCHED;
;             PG8_LDA(At, 1, 1); PG8_STAGE(PG8_SB(1, 0), b3, voffB); PG8_STAGE(PG8_SB(1, 1), b3 + hstepB, voffB); PG8_STAGE(PG8_SA(1, 0), a3, voffA);
;             PG8_WAIT_V(8); PG8_WAIT_L(0); PG8_BAR; PG8_MMA(1, 0, At, B0); PG8_MMA(1, 1, At, B1); PG8_BAR; PG8_SCHED;
;         }
;         if (wr == 0) PG8_BAR;
	s_add_i32 s56, 0, 0x18000
	s_add_i32 s57, 0, 0x1c000
	v_add_u32_e32 v162, s56, v145
	v_add_u32_e32 v178, s57, v145
	ds_read_b128 v[150:153], v162
	ds_read_b128 v[154:157], v162 offset:1024
	ds_read_b128 v[158:161], v162 offset:2048
	ds_read_b128 v[162:165], v162 offset:3072
	ds_read_b128 v[166:169], v178
	ds_read_b128 v[170:173], v178 offset:1024
	ds_read_b128 v[174:177], v178 offset:2048
	ds_read_b128 v[178:181], v178 offset:3072
	s_add_u32 s34, s34, 0x80000
	s_addc_u32 s35, s35, 0
	s_mov_b32 m0, s39
	ds_read_b128 v[182:185], v149 offset:32768
	ds_read_b128 v[186:189], v149 offset:33792
	ds_read_b128 v[192:195], v149 offset:34816
	ds_read_b128 v[196:199], v149 offset:35840
	ds_read_b128 v[200:203], v149 offset:36864
	ds_read_b128 v[204:207], v149 offset:37888
	ds_read_b128 v[208:211], v149 offset:38912
	ds_read_b128 v[212:215], v149 offset:39936
	global_load_lds_dwordx4 v134, s[34:35]
	s_mov_b32 m0, s40
	s_nop 0
	global_load_lds_dwordx4 v130, s[34:35]
	s_waitcnt vmcnt(8)
	s_waitcnt lgkmcnt(0)
	s_barrier
	s_setprio 1
	s_waitcnt lgkmcnt(0)
	v_mfma_f32_16x16x32_bf16 v[124:127], v[150:153], v[182:185], v[124:127]
	v_mfma_f32_16x16x32_bf16 v[120:123], v[158:161], v[182:185], v[120:123]
	v_mfma_f32_16x16x32_bf16 v[108:111], v[150:153], v[192:195], v[108:111]
	v_mfma_f32_16x16x32_bf16 v[104:107], v[158:161], v[192:195], v[104:107]
	v_mfma_f32_16x16x32_bf16 v[92:95], v[150:153], v[200:203], v[92:95]
	v_mfma_f32_16x16x32_bf16 v[88:91], v[158:161], v[200:203], v[88:91]
	v_mfma_f32_16x16x32_bf16 v[76:79], v[150:153], v[208:211], v[76:79]
	v_mfma_f32_16x16x32_bf16 v[72:75], v[158:161], v[208:211], v[72:75]
	v_mfma_f32_16x16x32_bf16 v[124:127], v[154:157], v[186:189], v[124:127]
	v_mfma_f32_16x16x32_bf16 v[120:123], v[162:165], v[186:189], v[120:123]
	v_mfma_f32_16x16x32_bf16 v[108:111], v[154:157], v[196:199], v[108:111]
	v_mfma_f32_16x16x32_bf16 v[104:107], v[162:165], v[196:199], v[104:107]
	v_mfma_f32_16x16x32_bf16 v[92:95], v[154:157], v[204:207], v[92:95]
	v_mfma_f32_16x16x32_bf16 v[88:91], v[162:165], v[204:207], v[88:91]
	v_mfma_f32_16x16x32_bf16 v[76:79], v[154:157], v[212:215], v[76:79]
	v_mfma_f32_16x16x32_bf16 v[72:75], v[162:165], v[212:215], v[72:75]
	v_mfma_f32_16x16x32_bf16 v[116:119], v[166:169], v[182:185], v[116:119]
	v_mfma_f32_16x16x32_bf16 v[112:115], v[174:177], v[182:185], v[112:115]
	v_mfma_f32_16x16x32_bf16 v[100:103], v[166:169], v[192:195], v[100:103]
	v_mfma_f32_16x16x32_bf16 v[96:99], v[174:177], v[192:195], v[96:99]
	v_mfma_f32_16x16x32_bf16 v[84:87], v[166:169], v[200:203], v[84:87]
	v_mfma_f32_16x16x32_bf16 v[80:83], v[174:177], v[200:203], v[80:83]
	v_mfma_f32_16x16x32_bf16 v[68:71], v[166:169], v[208:211], v[68:71]
	v_mfma_f32_16x16x32_bf16 v[64:67], v[174:177], v[208:211], v[64:67]
	v_mfma_f32_16x16x32_bf16 v[116:119], v[170:173], v[186:189], v[116:119]
	v_mfma_f32_16x16x32_bf16 v[112:115], v[178:181], v[186:189], v[112:115]
	v_mfma_f32_16x16x32_bf16 v[100:103], v[170:173], v[196:199], v[100:103]
	v_mfma_f32_16x16x32_bf16 v[96:99], v[178:181], v[196:199], v[96:99]
	v_mfma_f32_16x16x32_bf16 v[84:87], v[170:173], v[204:207], v[84:87]
	v_mfma_f32_16x16x32_bf16 v[80:83], v[178:181], v[204:207], v[80:83]
	v_mfma_f32_16x16x32_bf16 v[68:71], v[170:173], v[212:215], v[68:71]
	v_mfma_f32_16x16x32_bf16 v[64:67], v[178:181], v[212:215], v[64:67]
	s_setprio 0
	s_barrier
	s_add_i32 s34, s56, s36
	s_add_i32 m0, s34, 0xffffff80
	ds_read_b128 v[182:185], v149 offset:49152
	ds_read_b128 v[186:189], v149 offset:50176
	ds_read_b128 v[192:195], v149 offset:51200
	ds_read_b128 v[196:199], v149 offset:52224
	ds_read_b128 v[200:203], v149 offset:53248
	ds_read_b128 v[204:207], v149 offset:54272
	ds_read_b128 v[208:211], v149 offset:55296
	ds_read_b128 v[212:215], v149 offset:56320
	global_load_lds_dwordx4 v[216:217], off offset:128
	s_add_i32 m0, s34, 0x1f80
	s_add_u32 s30, s30, 0x80080
	s_addc_u32 s31, s31, 0
	s_add_i32 s34, s57, s36
	global_load_lds_dwordx4 v[218:219], off offset:128
	s_mov_b32 m0, s34
	s_nop 0
	global_load_lds_dwordx4 v132, s[30:31]
	s_add_i32 m0, s34, 0x2000
	s_nop 0
	global_load_lds_dwordx4 v128, s[30:31]
	s_add_i32 m0, s42, 0xffffff80
	s_nop 0
	global_load_lds_dwordx4 v[220:221], off offset:128
	s_add_i32 m0, s43, 0xffffff80
	s_nop 0
	global_load_lds_dwordx4 v[222:223], off offset:128
	s_waitcnt vmcnt(8)
	s_waitcnt lgkmcnt(0)
	s_barrier
	s_setprio 1
	s_waitcnt lgkmcnt(0)
	v_mfma_f32_16x16x32_bf16 v[60:63], v[150:153], v[182:185], v[60:63]
	v_mfma_f32_16x16x32_bf16 v[56:59], v[158:161], v[182:185], v[56:59]
	v_mfma_f32_16x16x32_bf16 v[44:47], v[150:153], v[192:195], v[44:47]
	v_mfma_f32_16x16x32_bf16 v[40:43], v[158:161], v[192:195], v[40:43]
	v_mfma_f32_16x16x32_bf16 v[28:31], v[150:153], v[200:203], v[28:31]
	v_mfma_f32_16x16x32_bf16 v[24:27], v[158:161], v[200:203], v[24:27]
	v_mfma_f32_16x16x32_bf16 v[12:15], v[150:153], v[208:211], v[12:15]
	v_mfma_f32_16x16x32_bf16 v[8:11], v[158:161], v[208:211], v[8:11]
	v_mfma_f32_16x16x32_bf16 v[60:63], v[154:157], v[186:189], v[60:63]
	v_mfma_f32_16x16x32_bf16 v[56:59], v[162:165], v[186:189], v[56:59]
	v_mfma_f32_16x16x32_bf16 v[44:47], v[154:157], v[196:199], v[44:47]
	v_mfma_f32_16x16x32_bf16 v[40:43], v[162:165], v[196:199], v[40:43]
	v_mfma_f32_16x16x32_bf16 v[28:31], v[154:157], v[204:207], v[28:31]
	v_mfma_f32_16x16x32_bf16 v[24:27], v[162:165], v[204:207], v[24:27]
	v_mfma_f32_16x16x32_bf16 v[12:15], v[154:157], v[212:215], v[12:15]
	v_mfma_f32_16x16x32_bf16 v[8:11], v[162:165], v[212:215], v[8:11]
	v_mfma_f32_16x16x32_bf16 v[52:55], v[166:169], v[182:185], v[52:55]
	v_mfma_f32_16x16x32_bf16 v[48:51], v[174:177], v[182:185], v[48:51]
	v_mfma_f32_16x16x32_bf16 v[36:39], v[166:169], v[192:195], v[36:39]
	v_mfma_f32_16x16x32_bf16 v[32:35], v[174:177], v[192:195], v[32:35]
	v_mfma_f32_16x16x32_bf16 v[20:23], v[166:169], v[200:203], v[20:23]
	v_mfma_f32_16x16x32_bf16 v[16:19], v[174:177], v[200:203], v[16:19]
	v_mfma_f32_16x16x32_bf16 v[4:7], v[166:169], v[208:211], v[4:7]
	v_mfma_f32_16x16x32_bf16 v[0:3], v[174:177], v[208:211], v[0:3]
	v_mfma_f32_16x16x32_bf16 v[52:55], v[170:173], v[186:189], v[52:55]
	v_mfma_f32_16x16x32_bf16 v[48:51], v[178:181], v[186:189], v[48:51]
	v_mfma_f32_16x16x32_bf16 v[36:39], v[170:173], v[196:199], v[36:39]
	v_mfma_f32_16x16x32_bf16 v[32:35], v[178:181], v[196:199], v[32:35]
	v_mfma_f32_16x16x32_bf16 v[20:23], v[170:173], v[204:207], v[20:23]
	v_mfma_f32_16x16x32_bf16 v[16:19], v[178:181], v[204:207], v[16:19]
	v_mfma_f32_16x16x32_bf16 v[4:7], v[170:173], v[212:215], v[4:7]
	v_mfma_f32_16x16x32_bf16 v[0:3], v[178:181], v[212:215], v[0:3]
	s_setprio 0
	s_barrier
	s_add_i32 s53, s53, 2
	s_add_u32 s28, s28, 0x100
	s_addc_u32 s29, s29, 0
	s_add_u32 s50, s50, 0x100
	s_addc_u32 s51, s51, 0
	s_cmp_gt_u32 s53, 29
	s_cbranch_scc0 .LBB0_954
	s_and_b64 vcc, exec, s[14:15]
	s_cbranch_vccz .LBB0_957
	s_barrier

; #define PG8_STAGE(bufoff, gbase, voff) do { _Pragma("unroll") for (int _i = 0; _i < 2; ++_i) \
;         __builtin_amdgcn_global_load_lds((const unsigned*)((const char*)(gbase) + (voff)[_i]), (LAS unsigned*)(lds + (bufoff) + ldsw + _i * 8192), 16, 0, 0); } while (0)
; #define PG8_LDA(dst, b, h) do { _Pragma("unroll") for (int m = 0; m < 4; ++m) _Pragma("unroll") for (int k = 0; k < 2; ++k) dst[m][k] = *(const LAS bf16x8*)(lds + PG8_SA(b, h) + aoff + m * 2048 + k * 1024); } while (0)
; #define PG8_LDB(dst, b, h) do { _Pragma("unroll") for (int n = 0; n < 2; ++n) _Pragma("unroll") for (int k = 0; k < 2; ++k) dst[n][k] = *(const LAS bf16x8*)(lds + PG8_SB(b, h) + boff + n * 2048 + k * 1024); } while (0)
; #define PG8_WAIT_V(n) asm volatile("s_waitcnt vmcnt(" #n ")" ::: "memory")
; #define PG8_WAIT_L(n) asm volatile("s_waitcnt lgkmcnt(" #n ")" ::: "memory")
; #define PG8_BAR __builtin_amdgcn_s_barrier()
; #define PG8_SCHED __builtin_amdgcn_sched_barrier(0)
; template <class Epi, class Sched, bool F8 = false>
; __device__ __forceinline__ void gemm_phase(LAS unsigned char* lds, const Gemm g, const Sched& S, const Epi& E) {
;     ...
;             const bool last = (t == nt - 2);
;             const char* a1 = cA + (size_t)(t + 1) * kstep;
;             const char* a2 = last ? nA : cA + (size_t)(t + 2) * kstep; const char* b2 = last ? nB : cB + (size_t)(t + 2) * kstep;
;             const char* a3 = a2 + kstep; const char* b3 = b2 + kstep;
;             PG8_LDB(B0, 0, 0); PG8_LDB(B1, 0, 1); PG8_SCHED; PG8_LDA(At, 0, 0); PG8_STAGE(PG8_SA(1, 1), a1 + hstepA, voffA);
;             PG8_WAIT_V(8); PG8_WAIT_L(0); PG8_BAR; PG8_MMA(0, 0, At, B0); PG8_MMA(0, 1, At, B1); PG8_BAR; PG8_SCHED;
;             PG8_LDA(At, 0, 1); PG8_STAGE(PG8_SB(0, 0), b2, voffB); PG8_STAGE(PG8_SB(0, 1), b2 + hstepB, voffB); PG8_STAGE(PG8_SA(0, 0), a2, voffA);
;             PG8_WAIT_V(8); PG8_WAIT_L(0); PG8_BAR; PG8_MMA(1, 0, At, B0); PG8_MMA(1, 1, At, B1); PG8_BAR; PG8_SCHED;
;             PG8_LDB(B0, 1, 0); PG8_LDB(B1, 1, 1); PG8_SCHED; PG8_LDA(At, 1, 0); PG8_STAGE(PG8_SA(0, 1), a2 + hstepA, voffA);
;             PG8_WAIT_V(8); PG8_WAIT_L(0); PG8_BAR; PG8_MMA(0, 0, At, B0); PG8_MMA(0, 1, At, B1); PG8_BAR; PG8_SCHED;
.LBB0_1030:
	ds_read_b128 v[144:147], v183
	ds_read_b128 v[148:151], v183 offset:1024
	ds_read_b128 v[152:155], v183 offset:2048
	ds_read_b128 v[156:159], v183 offset:3072
	ds_read_b128 v[160:163], v184
	ds_read_b128 v[164:167], v184 offset:1024
	ds_read_b128 v[168:171], v184 offset:2048
	ds_read_b128 v[172:175], v184 offset:3072
	s_add_u32 s28, s26, 0x100
	s_addc_u32 s29, s27, 0
	s_cmpk_eq_i32 s53, 0x54
	s_cselect_b32 s35, s9, s29
	s_cselect_b32 s34, s8, s28
	s_cselect_b32 s31, s25, s51
	s_cselect_b32 s30, s24, s50
	s_add_i32 m0, s37, 0xc000
	ds_read_b128 v[176:179], v185
	ds_read_b128 v[186:189], v185 offset:1024
	ds_read_b128 v[192:195], v185 offset:2048
	ds_read_b128 v[196:199], v185 offset:3072
	ds_read_b128 v[200:203], v185 offset:4096
	ds_read_b128 v[204:207], v185 offset:5120
	ds_read_b128 v[208:211], v185 offset:6144
	ds_read_b128 v[212:215], v185 offset:7168
	global_load_lds_dwordx4 v136, s[26:27]
	s_add_i32 m0, s37, 0xe000
	s_nop 0
	global_load_lds_dwordx4 v138, s[26:27]
	s_waitcnt vmcnt(8)
	s_waitcnt lgkmcnt(0)
	s_barrier
	s_setprio 1
	s_waitcnt lgkmcnt(0)
	v_mfma_f32_16x16x32_bf16 v[124:127], v[144:147], v[176:179], v[124:127]
	v_mfma_f32_16x16x32_bf16 v[120:123], v[152:155], v[176:179], v[120:123]
	v_mfma_f32_16x16x32_bf16 v[108:111], v[144:147], v[192:195], v[108:111]
	v_mfma_f32_16x16x32_bf16 v[104:107], v[152:155], v[192:195], v[104:107]
	v_mfma_f32_16x16x32_bf16 v[92:95], v[144:147], v[200:203], v[92:95]
	v_mfma_f32_16x16x32_bf16 v[88:91], v[152:155], v[200:203], v[88:91]
	v_mfma_f32_16x16x32_bf16 v[76:79], v[144:147], v[208:211], v[76:79]
	v_mfma_f32_16x16x32_bf16 v[72:75], v[152:155], v[208:211], v[72:75]
	v_mfma_f32_16x16x32_bf16 v[124:127], v[148:151], v[186:189], v[124:127]
	v_mfma_f32_16x16x32_bf16 v[120:123], v[156:159], v[186:189], v[120:123]
	v_mfma_f32_16x16x32_bf16 v[108:111], v[148:151], v[196:199], v[108:111]
	v_mfma_f32_16x16x32_bf16 v[104:107], v[156:159], v[196:199], v[104:107]
	v_mfma_f32_16x16x32_bf16 v[92:95], v[148:151], v[204:207], v[92:95]
	v_mfma_f32_16x16x32_bf16 v[88:91], v[156:159], v[204:207], v[88:91]
	v_mfma_f32_16x16x32_bf16 v[76:79], v[148:151], v[212:215], v[76:79]
	v_mfma_f32_16x16x32_bf16 v[72:75], v[156:159], v[212:215], v[72:75]
	v_mfma_f32_16x16x32_bf16 v[116:119], v[160:163], v[176:179], v[116:119]
	v_mfma_f32_16x16x32_bf16 v[112:115], v[168:171], v[176:179], v[112:115]
	v_mfma_f32_16x16x32_bf16 v[100:103], v[160:163], v[192:195], v[100:103]
	v_mfma_f32_16x16x32_bf16 v[96:99], v[168:171], v[192:195], v[96:99]
	v_mfma_f32_16x16x32_bf16 v[84:87], v[160:163], v[200:203], v[84:87]
	v_mfma_f32_16x16x32_bf16 v[80:83], v[168:171], v[200:203], v[80:83]
	v_mfma_f32_16x16x32_bf16 v[68:71], v[160:163], v[208:211], v[68:71]
	v_mfma_f32_16x16x32_bf16 v[64:67], v[168:171], v[208:211], v[64:67]
	v_mfma_f32_16x16x32_bf16 v[116:119], v[164:167], v[186:189], v[116:119]
	v_mfma_f32_16x16x32_bf16 v[112:115], v[172:175], v[186:189], v[112:115]
	v_mfma_f32_16x16x32_bf16 v[100:103], v[164:167], v[196:199], v[100:103]
	v_mfma_f32_16x16x32_bf16 v[96:99], v[172:175], v[196:199], v[96:99]
	v_mfma_f32_16x16x32_bf16 v[84:87], v[164:167], v[204:207], v[84:87]
	v_mfma_f32_16x16x32_bf16 v[80:83], v[172:175], v[204:207], v[80:83]
	v_mfma_f32_16x16x32_bf16 v[68:71], v[164:167], v[212:215], v[68:71]
	v_mfma_f32_16x16x32_bf16 v[64:67], v[172:175], v[212:215], v[64:67]
	s_setprio 0
	s_barrier
	s_add_i32 s26, s44, s23
	v_lshl_add_u64 v[216:217], s[30:31], 0, v[132:133]
	s_mov_b32 m0, s26
	ds_read_b128 v[176:179], v185 offset:16384
	ds_read_b128 v[186:189], v185 offset:17408
	ds_read_b128 v[192:195], v185 offset:18432
	ds_read_b128 v[196:199], v185 offset:19456
	ds_read_b128 v[200:203], v185 offset:20480
	ds_read_b128 v[204:207], v185 offset:21504
	ds_read_b128 v[208:211], v185 offset:22528
	ds_read_b128 v[212:215], v185 offset:23552
	global_load_lds_dwordx4 v[216:217], off
	s_add_i32 m0, s26, 0x2000
	s_add_u32 s26, s30, 0x160000
	v_lshl_add_u64 v[218:219], s[30:31], 0, v[128:129]
	s_addc_u32 s27, s31, 0
	s_add_i32 s56, s91, s23
	global_load_lds_dwordx4 v[218:219], off
	s_mov_b32 m0, s56
	v_lshl_add_u64 v[222:223], s[34:35], 0, v[130:131]
	global_load_lds_dwordx4 v132, s[26:27]
	s_add_i32 m0, s56, 0x2000
	s_nop 0
	global_load_lds_dwordx4 v128, s[26:27]
	v_lshl_add_u64 v[220:221], s[34:35], 0, v[134:135]
	s_mov_b32 m0, s37
	s_nop 0
	global_load_lds_dwordx4 v[220:221], off
	s_mov_b32 m0, s38
	s_nop 0
	global_load_lds_dwordx4 v[222:223], off
	s_waitcnt vmcnt(8)
	s_waitcnt lgkmcnt(0)
	s_barrier
	s_setprio 1
	s_waitcnt lgkmcnt(0)
	v_mfma_f32_16x16x32_bf16 v[60:63], v[144:147], v[176:179], v[60:63]
	v_mfma_f32_16x16x32_bf16 v[56:59], v[152:155], v[176:179], v[56:59]
	v_mfma_f32_16x16x32_bf16 v[44:47], v[144:147], v[192:195], v[44:47]
	v_mfma_f32_16x16x32_bf16 v[40:43], v[152:155], v[192:195], v[40:43]
	v_mfma_f32_16x16x32_bf16 v[28:31], v[144:147], v[200:203], v[28:31]
	v_mfma_f32_16x16x32_bf16 v[24:27], v[152:155], v[200:203], v[24:27]
	v_mfma_f32_16x16x32_bf16 v[12:15], v[144:147], v[208:211], v[12:15]
	v_mfma_f32_16x16x32_bf16 v[8:11], v[152:155], v[208:211], v[8:11]
	v_mfma_f32_16x16x32_bf16 v[60:63], v[148:151], v[186:189], v[60:63]
	v_mfma_f32_16x16x32_bf16 v[56:59], v[156:159], v[186:189], v[56:59]
	v_mfma_f32_16x16x32_bf16 v[44:47], v[148:151], v[196:199], v[44:47]
	v_mfma_f32_16x16x32_bf16 v[40:43], v[156:159], v[196:199], v[40:43]
	v_mfma_f32_16x16x32_bf16 v[28:31], v[148:151], v[204:207], v[28:31]
	v_mfma_f32_16x16x32_bf16 v[24:27], v[156:159], v[204:207], v[24:27]
	v_mfma_f32_16x16x32_bf16 v[12:15], v[148:151], v[212:215], v[12:15]
	v_mfma_f32_16x16x32_bf16 v[8:11], v[156:159], v[212:215], v[8:11]
	v_mfma_f32_16x16x32_bf16 v[52:55], v[160:163], v[176:179], v[52:55]
	v_mfma_f32_16x16x32_bf16 v[48:51], v[168:171], v[176:179], v[48:51]
	v_mfma_f32_16x16x32_bf16 v[36:39], v[160:163], v[192:195], v[36:39]
	v_mfma_f32_16x16x32_bf16 v[32:35], v[168:171], v[192:195], v[32:35]
	v_mfma_f32_16x16x32_bf16 v[20:23], v[160:163], v[200:203], v[20:23]
	v_mfma_f32_16x16x32_bf16 v[16:19], v[168:171], v[200:203], v[16:19]
	v_mfma_f32_16x16x32_bf16 v[4:7], v[160:163], v[208:211], v[4:7]
	v_mfma_f32_16x16x32_bf16 v[0:3], v[168:171], v[208:211], v[0:3]
	v_mfma_f32_16x16x32_bf16 v[52:55], v[164:167], v[186:189], v[52:55]
	v_mfma_f32_16x16x32_bf16 v[48:51], v[172:175], v[186:189], v[48:51]
	v_mfma_f32_16x16x32_bf16 v[36:39], v[164:167], v[196:199], v[36:39]
	v_mfma_f32_16x16x32_bf16 v[32:35], v[172:175], v[196:199], v[32:35]
	v_mfma_f32_16x16x32_bf16 v[20:23], v[164:167], v[204:207], v[20:23]
	v_mfma_f32_16x16x32_bf16 v[16:19], v[172:175], v[204:207], v[16:19]
	v_mfma_f32_16x16x32_bf16 v[4:7], v[164:167], v[212:215], v[4:7]
	v_mfma_f32_16x16x32_bf16 v[0:3], v[172:175], v[212:215], v[0:3]
	s_setprio 0
	s_barrier
; #define PG8_STAGE(bufoff, gbase, voff) do { _Pragma("unroll") for (int _i = 0; _i < 2; ++_i) \
;         __builtin_amdgcn_global_load_lds((const unsigned*)((const char*)(gbase) + (voff)[_i]), (LAS unsigned*)(lds + (bufoff) + ldsw + _i * 8192), 16, 0, 0); } while (0)
; #define PG8_LDA(dst, b, h) do { _Pragma("unroll") for (int m = 0; m < 4; ++m) _Pragma("unroll") for (int k = 0; k < 2; ++k) dst[m][k] = *(const LAS bf16x8*)(lds + PG8_SA(b, h) + aoff + m * 2048 + k * 1024); } while (0)
; #define PG8_WAIT_V(n) asm volatile("s_waitcnt vmcnt(" #n ")" ::: "memory")
; #define PG8_WAIT_L(n) asm volatile("s_waitcnt lgkmcnt(" #n ")" ::: "memory")
; #define PG8_BAR __builtin_amdgcn_s_barrier()
; #define PG8_SCHED __builtin_amdgcn_sched_barrier(0)
; template <class Epi, class Sched, bool F8 = false>
; __device__ __forceinline__ void gemm_phase(LAS unsigned char* lds, const Gemm g, const Sched& S, const Epi& E) {
;     ...
;             PG8_WAIT_V(8); PG8_WAIT_L(0); PG8_BAR; PG8_MMA(0, 0, At, B0); PG8_MMA(0, 1, At, B1); PG8_BAR; PG8_SCHED;
;             PG8_LDA(At, 1, 1); PG8_STAGE(PG8_SB(1, 0), b3, voffB); PG8_STAGE(PG8_SB(1, 1), b3 + hstepB, voffB); PG8_STAGE(PG8_SA(1, 0), a3, voffA);
;             PG8_WAIT_V(8); PG8_WAIT_L(0); PG8_BAR; PG8_MMA(1, 0, At, B0); PG8_MMA(1, 1, At, B1); PG8_BAR; PG8_SCHED;
;         }
;         if (wr == 0) PG8_BAR;
	s_add_i32 s56, 0, 0x18000
	s_add_i32 s57, 0, 0x1c000
	v_add_u32_e32 v156, s56, v181
	v_add_u32_e32 v172, s57, v181
	ds_read_b128 v[144:147], v156
	ds_read_b128 v[148:151], v156 offset:1024
	ds_read_b128 v[152:155], v156 offset:2048
	ds_read_b128 v[156:159], v156 offset:3072
	ds_read_b128 v[160:163], v172
	ds_read_b128 v[164:167], v172 offset:1024
	ds_read_b128 v[168:171], v172 offset:2048
	ds_read_b128 v[172:175], v172 offset:3072
	s_add_u32 s26, s34, 0x160000
	s_addc_u32 s27, s35, 0
	s_mov_b32 m0, s39
	ds_read_b128 v[176:179], v185 offset:32768
	ds_read_b128 v[186:189], v185 offset:33792
	ds_read_b128 v[192:195], v185 offset:34816
	ds_read_b128 v[196:199], v185 offset:35840
	ds_read_b128 v[200:203], v185 offset:36864
	ds_read_b128 v[204:207], v185 offset:37888
	ds_read_b128 v[208:211], v185 offset:38912
	ds_read_b128 v[212:215], v185 offset:39936
	global_load_lds_dwordx4 v134, s[26:27]
	s_mov_b32 m0, s40
	s_nop 0
	global_load_lds_dwordx4 v130, s[26:27]
	s_waitcnt vmcnt(8)
	s_waitcnt lgkmcnt(0)
	s_barrier
	s_setprio 1
	s_waitcnt lgkmcnt(0)
	v_mfma_f32_16x16x32_bf16 v[124:127], v[144:147], v[176:179], v[124:127]
	v_mfma_f32_16x16x32_bf16 v[120:123], v[152:155], v[176:179], v[120:123]
	v_mfma_f32_16x16x32_bf16 v[108:111], v[144:147], v[192:195], v[108:111]
	v_mfma_f32_16x16x32_bf16 v[104:107], v[152:155], v[192:195], v[104:107]
	v_mfma_f32_16x16x32_bf16 v[92:95], v[144:147], v[200:203], v[92:95]
	v_mfma_f32_16x16x32_bf16 v[88:91], v[152:155], v[200:203], v[88:91]
	v_mfma_f32_16x16x32_bf16 v[76:79], v[144:147], v[208:211], v[76:79]
	v_mfma_f32_16x16x32_bf16 v[72:75], v[152:155], v[208:211], v[72:75]
	v_mfma_f32_16x16x32_bf16 v[124:127], v[148:151], v[186:189], v[124:127]
	v_mfma_f32_16x16x32_bf16 v[120:123], v[156:159], v[186:189], v[120:123]
	v_mfma_f32_16x16x32_bf16 v[108:111], v[148:151], v[196:199], v[108:111]
	v_mfma_f32_16x16x32_bf16 v[104:107], v[156:159], v[196:199], v[104:107]
	v_mfma_f32_16x16x32_bf16 v[92:95], v[148:151], v[204:207], v[92:95]
	v_mfma_f32_16x16x32_bf16 v[88:91], v[156:159], v[204:207], v[88:91]
	v_mfma_f32_16x16x32_bf16 v[76:79], v[148:151], v[212:215], v[76:79]
	v_mfma_f32_16x16x32_bf16 v[72:75], v[156:159], v[212:215], v[72:75]
	v_mfma_f32_16x16x32_bf16 v[116:119], v[160:163], v[176:179], v[116:119]
	v_mfma_f32_16x16x32_bf16 v[112:115], v[168:171], v[176:179], v[112:115]
	v_mfma_f32_16x16x32_bf16 v[100:103], v[160:163], v[192:195], v[100:103]
	v_mfma_f32_16x16x32_bf16 v[96:99], v[168:171], v[192:195], v[96:99]
	v_mfma_f32_16x16x32_bf16 v[84:87], v[160:163], v[200:203], v[84:87]
	v_mfma_f32_16x16x32_bf16 v[80:83], v[168:171], v[200:203], v[80:83]
	v_mfma_f32_16x16x32_bf16 v[68:71], v[160:163], v[208:211], v[68:71]
	v_mfma_f32_16x16x32_bf16 v[64:67], v[168:171], v[208:211], v[64:67]
	v_mfma_f32_16x16x32_bf16 v[116:119], v[164:167], v[186:189], v[116:119]
	v_mfma_f32_16x16x32_bf16 v[112:115], v[172:175], v[186:189], v[112:115]
	v_mfma_f32_16x16x32_bf16 v[100:103], v[164:167], v[196:199], v[100:103]
	v_mfma_f32_16x16x32_bf16 v[96:99], v[172:175], v[196:199], v[96:99]
	v_mfma_f32_16x16x32_bf16 v[84:87], v[164:167], v[204:207], v[84:87]
	v_mfma_f32_16x16x32_bf16 v[80:83], v[172:175], v[204:207], v[80:83]
	v_mfma_f32_16x16x32_bf16 v[68:71], v[164:167], v[212:215], v[68:71]
	v_mfma_f32_16x16x32_bf16 v[64:67], v[172:175], v[212:215], v[64:67]
	s_setprio 0
	s_barrier
	s_add_i32 s26, s56, s23
	s_add_i32 m0, s26, 0xffffff80
	ds_read_b128 v[176:179], v185 offset:49152
	ds_read_b128 v[186:189], v185 offset:50176
	ds_read_b128 v[192:195], v185 offset:51200
	ds_read_b128 v[196:199], v185 offset:52224
	ds_read_b128 v[200:203], v185 offset:53248
	ds_read_b128 v[204:207], v185 offset:54272
	ds_read_b128 v[208:211], v185 offset:55296
	ds_read_b128 v[212:215], v185 offset:56320
	global_load_lds_dwordx4 v[216:217], off offset:128
	s_add_i32 m0, s26, 0x1f80
	s_add_u32 s26, s30, 0x160080
	s_addc_u32 s27, s31, 0
	s_add_i32 s30, s57, s23
	global_load_lds_dwordx4 v[218:219], off offset:128
	s_mov_b32 m0, s30
	s_nop 0
	global_load_lds_dwordx4 v132, s[26:27]
	s_add_i32 m0, s30, 0x2000
	s_nop 0
	global_load_lds_dwordx4 v128, s[26:27]
	s_add_i32 m0, s42, 0xffffff80
	s_nop 0
	global_load_lds_dwordx4 v[220:221], off offset:128
	s_add_i32 m0, s43, 0xffffff80
	s_nop 0
	global_load_lds_dwordx4 v[222:223], off offset:128
	s_waitcnt vmcnt(8)
	s_waitcnt lgkmcnt(0)
	s_barrier
	s_setprio 1
	s_waitcnt lgkmcnt(0)
	v_mfma_f32_16x16x32_bf16 v[60:63], v[144:147], v[176:179], v[60:63]
	v_mfma_f32_16x16x32_bf16 v[56:59], v[152:155], v[176:179], v[56:59]
	v_mfma_f32_16x16x32_bf16 v[44:47], v[144:147], v[192:195], v[44:47]
	v_mfma_f32_16x16x32_bf16 v[40:43], v[152:155], v[192:195], v[40:43]
	v_mfma_f32_16x16x32_bf16 v[28:31], v[144:147], v[200:203], v[28:31]
	v_mfma_f32_16x16x32_bf16 v[24:27], v[152:155], v[200:203], v[24:27]
	v_mfma_f32_16x16x32_bf16 v[12:15], v[144:147], v[208:211], v[12:15]
	v_mfma_f32_16x16x32_bf16 v[8:11], v[152:155], v[208:211], v[8:11]
	v_mfma_f32_16x16x32_bf16 v[60:63], v[148:151], v[186:189], v[60:63]
	v_mfma_f32_16x16x32_bf16 v[56:59], v[156:159], v[186:189], v[56:59]
	v_mfma_f32_16x16x32_bf16 v[44:47], v[148:151], v[196:199], v[44:47]
	v_mfma_f32_16x16x32_bf16 v[40:43], v[156:159], v[196:199], v[40:43]
	v_mfma_f32_16x16x32_bf16 v[28:31], v[148:151], v[204:207], v[28:31]
	v_mfma_f32_16x16x32_bf16 v[24:27], v[156:159], v[204:207], v[24:27]
	v_mfma_f32_16x16x32_bf16 v[12:15], v[148:151], v[212:215], v[12:15]
	v_mfma_f32_16x16x32_bf16 v[8:11], v[156:159], v[212:215], v[8:11]
	v_mfma_f32_16x16x32_bf16 v[52:55], v[160:163], v[176:179], v[52:55]
	v_mfma_f32_16x16x32_bf16 v[48:51], v[168:171], v[176:179], v[48:51]
	v_mfma_f32_16x16x32_bf16 v[36:39], v[160:163], v[192:195], v[36:39]
	v_mfma_f32_16x16x32_bf16 v[32:35], v[168:171], v[192:195], v[32:35]
	v_mfma_f32_16x16x32_bf16 v[20:23], v[160:163], v[200:203], v[20:23]
	v_mfma_f32_16x16x32_bf16 v[16:19], v[168:171], v[200:203], v[16:19]
	v_mfma_f32_16x16x32_bf16 v[4:7], v[160:163], v[208:211], v[4:7]
	v_mfma_f32_16x16x32_bf16 v[0:3], v[168:171], v[208:211], v[0:3]
	v_mfma_f32_16x16x32_bf16 v[52:55], v[164:167], v[186:189], v[52:55]
	v_mfma_f32_16x16x32_bf16 v[48:51], v[172:175], v[186:189], v[48:51]
	v_mfma_f32_16x16x32_bf16 v[36:39], v[164:167], v[196:199], v[36:39]
	v_mfma_f32_16x16x32_bf16 v[32:35], v[172:175], v[196:199], v[32:35]
	v_mfma_f32_16x16x32_bf16 v[20:23], v[164:167], v[204:207], v[20:23]
	v_mfma_f32_16x16x32_bf16 v[16:19], v[172:175], v[204:207], v[16:19]
	v_mfma_f32_16x16x32_bf16 v[4:7], v[164:167], v[212:215], v[4:7]
	v_mfma_f32_16x16x32_bf16 v[0:3], v[172:175], v[212:215], v[0:3]
	s_setprio 0
	s_barrier
	s_add_i32 s53, s53, 2
	s_add_u32 s50, s50, 0x100
	s_addc_u32 s51, s51, 0
	s_cmpk_gt_u32 s53, 0x55
	s_mov_b64 s[26:27], s[28:29]
	s_cbranch_scc0 .LBB0_1030
	s_and_b64 vcc, exec, s[20:21]
	s_cbranch_vccz .LBB0_1033
	s_barrier
